# ds_bpermute butterfly reductions replaced by DPP/permlane-swap adds in attention subln finalize and P1/P6/P9 LayerNorm loops (same pairings)
# baseline (speedup 1.0000x reference)
; #define GAS __attribute__((address_space(1)))
; #define LAS __attribute__((address_space(3)))
; __device__ __forceinline__ unsigned pk2(float lo, float hi) { return f2bf(lo) | (f2bf(hi) << 16); }
; __device__ __forceinline__ float wave_sum(float v, int lane) {
; #pragma unroll
;     for (int o = 1; o < 64; o <<= 1) v += __builtin_bit_cast(float, __builtin_amdgcn_ds_bpermute((lane ^ o) << 2, __builtin_bit_cast(int, v)));
;     return v;
; }
; __global__ void __launch_bounds__(NWAVES * 64) mega_fwd(Args args) {
;     ...
;             for (int rr = wave; rr < 256; rr += NWAVES) {
;                 const size_t row = (size_t)p * 256 + rr;
;                 const GAS f32x4* xr = (const GAS f32x4*)(x + row * D) + lane;
;                 f32x4 v[4]; float s = 0.f;
; #pragma unroll
;                 for (int j = 0; j < 4; ++j) { v[j] = __builtin_nontemporal_load(&xr[64 * j]); s += (v[j].x + v[j].y) + (v[j].z + v[j].w); }
;                 const float mean = wave_sum(s, lane) * (1.f / D); float s2 = 0.f;
; #pragma unroll
;                 for (int j = 0; j < 4; ++j) { v[j] = v[j] - mean; s2 += (v[j].x * v[j].x + v[j].y * v[j].y) + (v[j].z * v[j].z + v[j].w * v[j].w); }
;                 const float rstd = 1.f / sqrtf(wave_sum(s2, lane) * (1.f / D) + LN_EPS);
;                 GAS unsigned long long* o8 = (GAS unsigned long long*)(HB + row * D) + lane;
; #pragma unroll
;                 for (int j = 0; j < 4; ++j) { const f32x4 sh = *(const LAS f32x4*)(shsc + 256 * j + 4 * lane), sc = *(const LAS f32x4*)(shsc + 1024 + 256 * j + 4 * lane);
;                     const f32x4 y = v[j] * rstd * (sc + 1.0f) + sh;
;                     o8[64 * j] = (unsigned long long)pk2(y.x, y.y) | ((unsigned long long)pk2(y.z, y.w) << 32); }
.LBB0_135:
	global_load_dwordx4 v[16:19], v[54:55], off offset:-3072 nt
	global_load_dwordx4 v[20:23], v[54:55], off offset:-2048 nt
	global_load_dwordx4 v[24:27], v[54:55], off offset:-1024 nt
	global_load_dwordx4 v[28:31], v[54:55], off nt
	s_mov_b64 s[0:1], 0x8000
	v_lshl_add_u64 v[54:55], v[54:55], 0, s[0:1]
	s_add_i32 s31, s31, 8
	s_cmpk_gt_i32 s31, 0xf7
	s_waitcnt vmcnt(3)
	v_mov_b32_e32 v72, v17
	v_mov_b32_e32 v73, v18
	v_mov_b32_e32 v74, v16
	v_mov_b32_e32 v75, v19
	s_waitcnt vmcnt(2)
	v_mov_b32_e32 v76, v21
	v_mov_b32_e32 v77, v22
	v_mov_b32_e32 v78, v20
	v_mov_b32_e32 v79, v23
	v_pk_add_f32 v[72:73], v[72:73], v[74:75]
	v_pk_add_f32 v[74:75], v[76:77], v[78:79]
	v_add_f32_e32 v78, v72, v73
	v_pk_add_f32 v[72:73], v[74:75], v[74:75] op_sel:[0,1] op_sel_hi:[1,0]
	s_waitcnt vmcnt(1)
	v_add_f32_e32 v80, v24, v25
	v_add_f32_e32 v82, v26, v27
	s_waitcnt vmcnt(0)
	v_mov_b32_e32 v85, v28
	v_mov_b32_e32 v81, v30
	v_mov_b32_e32 v83, v31
	v_add_f32_e32 v84, 0, v78
	v_mov_b32_e32 v73, v29
	v_pk_add_f32 v[76:77], v[80:81], v[82:83]
	v_pk_add_f32 v[72:73], v[84:85], v[72:73]
	s_nop 0
	v_pk_add_f32 v[72:73], v[72:73], v[76:77]
	s_nop 0
	v_add_f32_e32 v72, v72, v73
	s_waitcnt lgkmcnt(0)
	s_nop 1
	v_add_f32_dpp v72, v72, v72 quad_perm:[1,0,3,2] row_mask:0xf bank_mask:0xf
	s_waitcnt lgkmcnt(0)
	s_nop 1
	v_add_f32_dpp v72, v72, v72 quad_perm:[2,3,0,1] row_mask:0xf bank_mask:0xf
	s_waitcnt lgkmcnt(0)
	s_nop 1
	v_add_f32_dpp v72, v72, v72 row_half_mirror row_mask:0xf bank_mask:0xf
	s_waitcnt lgkmcnt(0)
	s_nop 1
	v_add_f32_dpp v72, v72, v72 row_mirror row_mask:0xf bank_mask:0xf
	s_waitcnt lgkmcnt(0)
	v_mov_b32_e32 v73, v72
	s_nop 1
	v_permlane16_swap_b32_e32 v72, v73
	v_add_f32_e32 v72, v72, v73
	s_waitcnt lgkmcnt(0)
	v_mov_b32_e32 v73, v72
	s_nop 1
	v_permlane32_swap_b32_e32 v72, v73
	v_add_f32_e32 v72, v72, v73
	v_fmamk_f32 v17, v72, 0xba800000, v17
	v_fmamk_f32 v16, v72, 0xba800000, v16
	v_fmamk_f32 v19, v72, 0xba800000, v19
	v_fmac_f32_e32 v18, 0xba800000, v72
	v_fmamk_f32 v21, v72, 0xba800000, v21
	v_fmamk_f32 v20, v72, 0xba800000, v20
	v_fmamk_f32 v23, v72, 0xba800000, v23
	v_fmac_f32_e32 v22, 0xba800000, v72
	v_fmamk_f32 v25, v72, 0xba800000, v25
	v_fmamk_f32 v24, v72, 0xba800000, v24
	v_fmamk_f32 v27, v72, 0xba800000, v27
	v_fmac_f32_e32 v26, 0xba800000, v72
	v_fmamk_f32 v31, v72, 0xba800000, v31
	v_fmamk_f32 v30, v72, 0xba800000, v30
	v_fmamk_f32 v29, v72, 0xba800000, v29
	v_fmac_f32_e32 v28, 0xba800000, v72
	v_pk_mul_f32 v[72:73], v[18:19], v[18:19]
	v_pk_mul_f32 v[74:75], v[16:17], v[16:17]
	v_pk_mul_f32 v[76:77], v[22:23], v[22:23]
	v_pk_mul_f32 v[78:79], v[20:21], v[20:21]
	v_pk_mov_b32 v[84:85], v[74:75], v[72:73] op_sel:[1,0]
	v_mov_b32_e32 v75, v73
	v_pk_mov_b32 v[72:73], v[78:79], v[76:77] op_sel:[1,0]
	v_mov_b32_e32 v79, v77
	v_mul_f32_e32 v83, v28, v28
	v_mul_f32_e32 v80, v25, v25
	v_mul_f32_e32 v82, v27, v27
	v_pk_add_f32 v[74:75], v[84:85], v[74:75]
	v_pk_add_f32 v[72:73], v[72:73], v[78:79]
	v_mul_f32_e32 v86, v29, v29
	v_mul_f32_e32 v87, v30, v30
	v_mul_f32_e32 v88, v31, v31
	v_pk_fma_f32 v[76:77], v[24:25], v[24:25], v[80:81] op_sel_hi:[1,1,0]
	v_pk_fma_f32 v[80:81], v[26:27], v[26:27], v[82:83] op_sel_hi:[1,1,0]
	v_pk_add_f32 v[74:75], v[74:75], v[74:75] op_sel:[0,1] op_sel_hi:[1,0]
	v_pk_add_f32 v[72:73], v[72:73], v[72:73] op_sel:[0,1] op_sel_hi:[1,0]
	v_mov_b32_e32 v77, v87
	v_mov_b32_e32 v81, v88
	v_mov_b32_e32 v75, v83
	v_mov_b32_e32 v73, v86
	v_pk_add_f32 v[76:77], v[76:77], v[80:81]
	v_pk_add_f32 v[72:73], v[74:75], v[72:73]
	s_nop 0
	v_pk_add_f32 v[72:73], v[72:73], v[76:77]
	s_nop 0
	v_add_f32_e32 v72, v72, v73
	s_waitcnt lgkmcnt(0)
	s_nop 1
	v_add_f32_dpp v72, v72, v72 quad_perm:[1,0,3,2] row_mask:0xf bank_mask:0xf
	s_waitcnt lgkmcnt(0)
	s_nop 1
	v_add_f32_dpp v72, v72, v72 quad_perm:[2,3,0,1] row_mask:0xf bank_mask:0xf
	s_waitcnt lgkmcnt(0)
	s_nop 1
	v_add_f32_dpp v72, v72, v72 row_half_mirror row_mask:0xf bank_mask:0xf
	s_waitcnt lgkmcnt(0)
; #define GAS __attribute__((address_space(1)))
; #define LAS __attribute__((address_space(3)))
; __device__ __forceinline__ unsigned pk2(float lo, float hi) { return f2bf(lo) | (f2bf(hi) << 16); }
; __global__ void __launch_bounds__(NWAVES * 64) mega_fwd(Args args) {
;     ...
;                 const float rstd = 1.f / sqrtf(wave_sum(s2, lane) * (1.f / D) + LN_EPS);
;                 GAS unsigned long long* o8 = (GAS unsigned long long*)(HB + row * D) + lane;
; #pragma unroll
;                 for (int j = 0; j < 4; ++j) { const f32x4 sh = *(const LAS f32x4*)(shsc + 256 * j + 4 * lane), sc = *(const LAS f32x4*)(shsc + 1024 + 256 * j + 4 * lane);
;                     const f32x4 y = v[j] * rstd * (sc + 1.0f) + sh;
;                     o8[64 * j] = (unsigned long long)pk2(y.x, y.y) | ((unsigned long long)pk2(y.z, y.w) << 32); }
	s_nop 1
	v_add_f32_dpp v72, v72, v72 row_mirror row_mask:0xf bank_mask:0xf
	s_waitcnt lgkmcnt(0)
	v_mov_b32_e32 v73, v72
	s_nop 1
	v_permlane16_swap_b32_e32 v72, v73
	v_add_f32_e32 v72, v72, v73
	s_waitcnt lgkmcnt(0)
	v_mov_b32_e32 v73, v72
	s_nop 1
	v_permlane32_swap_b32_e32 v72, v73
	v_add_f32_e32 v72, v72, v73
	v_fmamk_f32 v72, v72, 0x3a800000, v70
	v_mul_f32_e32 v73, 0x4f800000, v72
	v_cmp_gt_f32_e32 vcc, s33, v72
	s_nop 1
	v_cndmask_b32_e32 v72, v72, v73, vcc
	v_sqrt_f32_e32 v73, v72
	s_nop 0
	v_add_u32_e32 v74, -1, v73
	v_add_u32_e32 v75, 1, v73
	v_fma_f32 v76, -v74, v73, v72
	v_fma_f32 v77, -v75, v73, v72
	v_cmp_ge_f32_e64 s[0:1], 0, v76
	s_nop 1
	v_cndmask_b32_e64 v73, v73, v74, s[0:1]
	v_cmp_lt_f32_e64 s[0:1], 0, v77
	s_nop 1
	v_cndmask_b32_e64 v73, v73, v75, s[0:1]
	v_mul_f32_e32 v74, 0x37800000, v73
	v_cndmask_b32_e32 v73, v73, v74, vcc
	v_cmp_class_f32_e32 vcc, v72, v71
	s_nop 1
	v_cndmask_b32_e32 v72, v73, v72, vcc
	v_div_scale_f32 v73, s[0:1], v72, v72, 1.0
	v_rcp_f32_e32 v75, v73
	v_div_scale_f32 v74, vcc, 1.0, v72, 1.0
	v_fma_f32 v76, -v73, v75, 1.0
	v_fmac_f32_e32 v75, v76, v75
	v_mul_f32_e32 v76, v74, v75
	v_fma_f32 v77, -v73, v76, v74
	v_fmac_f32_e32 v76, v77, v75
	v_fma_f32 v73, -v73, v76, v74
	v_div_fmas_f32 v73, v73, v75, v76
	v_div_fixup_f32 v72, v73, v72, 1.0
	v_pk_mul_f32 v[16:17], v[72:73], v[16:17] op_sel_hi:[0,1]
	v_pk_mul_f32 v[18:19], v[72:73], v[18:19] op_sel_hi:[0,1]
	v_pk_mul_f32 v[20:21], v[72:73], v[20:21] op_sel_hi:[0,1]
	v_pk_mul_f32 v[22:23], v[72:73], v[22:23] op_sel_hi:[0,1]
	v_pk_mul_f32 v[24:25], v[72:73], v[24:25] op_sel_hi:[0,1]
	v_pk_mul_f32 v[26:27], v[72:73], v[26:27] op_sel_hi:[0,1]
	v_pk_mul_f32 v[28:29], v[72:73], v[28:29] op_sel_hi:[0,1]
	v_pk_mul_f32 v[30:31], v[72:73], v[30:31] op_sel_hi:[0,1]
	v_pk_fma_f32 v[18:19], v[18:19], v[36:37], v[2:3]
	v_pk_fma_f32 v[16:17], v[16:17], v[38:39], v[0:1]
	v_pk_fma_f32 v[22:23], v[22:23], v[40:41], v[6:7]
	v_pk_fma_f32 v[20:21], v[20:21], v[42:43], v[4:5]
	v_pk_fma_f32 v[26:27], v[26:27], v[44:45], v[10:11]
	v_pk_fma_f32 v[24:25], v[24:25], v[46:47], v[8:9]
	v_pk_fma_f32 v[30:31], v[30:31], v[48:49], v[14:15]
	v_pk_fma_f32 v[28:29], v[28:29], v[50:51], v[12:13]
	v_bfe_u32 v72, v16, 16, 1
	v_bfe_u32 v74, v18, 16, 1
	v_bfe_u32 v73, v17, 16, 1
	v_bfe_u32 v75, v19, 16, 1
	v_bfe_u32 v76, v20, 16, 1
	v_bfe_u32 v78, v22, 16, 1
	v_bfe_u32 v80, v24, 16, 1
	v_bfe_u32 v82, v26, 16, 1
	v_bfe_u32 v84, v28, 16, 1
	v_bfe_u32 v86, v30, 16, 1
	v_add3_u32 v16, v16, v72, s23
	v_add3_u32 v18, v18, v74, s23
	v_bfe_u32 v77, v21, 16, 1
	v_bfe_u32 v79, v23, 16, 1
	v_bfe_u32 v81, v25, 16, 1
	v_bfe_u32 v83, v27, 16, 1
	v_bfe_u32 v85, v29, 16, 1
	v_bfe_u32 v87, v31, 16, 1
	v_add3_u32 v17, v17, v73, s23
	v_add3_u32 v19, v19, v75, s23
	v_add3_u32 v20, v20, v76, s23
	v_add3_u32 v22, v22, v78, s23
	v_add3_u32 v24, v24, v80, s23
	v_add3_u32 v26, v26, v82, s23
	v_add3_u32 v28, v28, v84, s23
	v_add3_u32 v30, v30, v86, s23
	v_lshrrev_b32_e32 v16, 16, v16
	v_lshrrev_b32_e32 v18, 16, v18
	v_add3_u32 v21, v21, v77, s23
	v_add3_u32 v23, v23, v79, s23
	v_add3_u32 v25, v25, v81, s23
	v_add3_u32 v27, v27, v83, s23
	v_add3_u32 v29, v29, v85, s23
	v_add3_u32 v31, v31, v87, s23
	v_lshrrev_b32_e32 v20, 16, v20
	v_lshrrev_b32_e32 v22, 16, v22
	v_lshrrev_b32_e32 v24, 16, v24
	v_lshrrev_b32_e32 v26, 16, v26
	v_lshrrev_b32_e32 v28, 16, v28
	v_lshrrev_b32_e32 v30, 16, v30
	v_and_or_b32 v16, v17, s27, v16
	v_and_or_b32 v17, v19, s27, v18
	v_and_or_b32 v18, v21, s27, v20
	v_and_or_b32 v19, v23, s27, v22
	v_and_or_b32 v20, v25, s27, v24
	v_and_or_b32 v21, v27, s27, v26
	v_and_or_b32 v22, v29, s27, v28
	v_and_or_b32 v23, v31, s27, v30
	global_store_dwordx2 v[52:53], v[16:17], off offset:-1024
	global_store_dwordx2 v[52:53], v[18:19], off offset:-512
	global_store_dwordx2 v[52:53], v[20:21], off
	global_store_dwordx2 v[52:53], v[22:23], off offset:512
	v_lshl_add_u64 v[52:53], v[52:53], 0, s[56:57]
	s_cbranch_scc0 .LBB0_135
	s_branch .LBB0_112

; __device__ __forceinline__ void attn_unit_pp(int b, int h, int qb, int par, const bf16_t* __restrict__ QBp, const bf16_t* __restrict__ KBp, const bf16_t* __restrict__ VBp, ...
;     ...
;     unsigned gate16[64];
; #pragma unroll
;     for (int r = 0; r < 16; ++r)
; #pragma unroll
;       for (int d0 = 0; d0 < 4; ++d0) gate16[r * 4 + d0] = GATE_LD((r & 3) + 8 * (r >> 2), d0 * 32);
;     __syncthreads();
.LBB0_411:
	v_add_u32_e32 v36, 64, v34
	v_add_u32_e32 v37, 0x80, v34
	v_add_u32_e32 v38, 0xc0, v34
	v_add_u32_e32 v39, 0x1000, v34
	v_add_u32_e32 v40, 0x1040, v34
	v_add_u32_e32 v41, 0x1080, v34
	v_add_u32_e32 v42, 0x10c0, v34
	global_load_ushort v165, v34, s[20:21]
	global_load_ushort v163, v36, s[20:21]
	global_load_ushort v162, v37, s[20:21]
	global_load_ushort v159, v38, s[20:21]
	global_load_ushort v157, v39, s[20:21]
	global_load_ushort v154, v40, s[20:21]
	global_load_ushort v152, v41, s[20:21]
	global_load_ushort v149, v42, s[20:21]
	v_add_u32_e32 v36, 0x2000, v34
	v_add_u32_e32 v37, 0x2040, v34
	v_add_u32_e32 v38, 0x2080, v34
	v_add_u32_e32 v39, 0x20c0, v34
	v_add_u32_e32 v43, 0x30c0, v34
	v_add_u32_e32 v40, 0x3000, v34
	v_add_u32_e32 v41, 0x3040, v34
	v_add_u32_e32 v42, 0x3080, v34
	global_load_ushort v151, v36, s[20:21]
	global_load_ushort v148, v37, s[20:21]
	global_load_ushort v147, v38, s[20:21]
	global_load_ushort v143, v39, s[20:21]
	global_load_ushort v141, v40, s[20:21]
	global_load_ushort v139, v41, s[20:21]
	global_load_ushort v138, v42, s[20:21]
	global_load_ushort v134, v43, s[20:21]
	v_add_u32_e32 v36, 0x8000, v34
	v_add_u32_e32 v37, 0x8040, v34
	v_add_u32_e32 v38, 0x8080, v34
	v_add_u32_e32 v39, 0x80c0, v34
	v_add_u32_e32 v43, 0x90c0, v34
	v_add_u32_e32 v40, 0x9000, v34
	v_add_u32_e32 v41, 0x9040, v34
	v_add_u32_e32 v42, 0x9080, v34
	global_load_ushort v137, v36, s[20:21]
	global_load_ushort v133, v37, s[20:21]
	global_load_ushort v131, v38, s[20:21]
	global_load_ushort v130, v39, s[20:21]
	global_load_ushort v129, v40, s[20:21]
	global_load_ushort v126, v41, s[20:21]
	global_load_ushort v124, v42, s[20:21]
	global_load_ushort v122, v43, s[20:21]
	v_add_u32_e32 v36, 0xa000, v34
	v_add_u32_e32 v37, 0xa040, v34
	v_add_u32_e32 v38, 0xa080, v34
	v_add_u32_e32 v39, 0xa0c0, v34
	v_add_u32_e32 v43, 0xb0c0, v34
	v_add_u32_e32 v40, 0xb000, v34
	v_add_u32_e32 v41, 0xb040, v34
	v_add_u32_e32 v42, 0xb080, v34
	global_load_ushort v123, v36, s[20:21]
	global_load_ushort v121, v37, s[20:21]
	global_load_ushort v120, v38, s[20:21]
	global_load_ushort v117, v39, s[20:21]
	global_load_ushort v115, v40, s[20:21]
	global_load_ushort v114, v41, s[20:21]
	global_load_ushort v113, v42, s[20:21]
	global_load_ushort v109, v43, s[20:21]
	v_add_u32_e32 v36, 0x10000, v34
	v_add_u32_e32 v37, 0x10040, v34
	v_add_u32_e32 v38, 0x10080, v34
	v_add_u32_e32 v39, 0x100c0, v34
	v_add_u32_e32 v43, 0x110c0, v34
	v_add_u32_e32 v40, 0x11000, v34
	v_add_u32_e32 v41, 0x11040, v34
	v_add_u32_e32 v42, 0x11080, v34
	global_load_ushort v110, v36, s[20:21]
	global_load_ushort v108, v37, s[20:21]
	global_load_ushort v106, v38, s[20:21]
	global_load_ushort v105, v39, s[20:21]
	global_load_ushort v104, v40, s[20:21]
	global_load_ushort v102, v41, s[20:21]
	global_load_ushort v65, v42, s[20:21]
	global_load_ushort v63, v43, s[20:21]
	v_add_u32_e32 v36, 0x12000, v34
	v_add_u32_e32 v37, 0x12040, v34
	v_add_u32_e32 v38, 0x12080, v34
	v_add_u32_e32 v39, 0x120c0, v34
	v_add_u32_e32 v43, 0x130c0, v34
	v_add_u32_e32 v40, 0x13000, v34
	v_add_u32_e32 v41, 0x13040, v34
	v_add_u32_e32 v42, 0x13080, v34
	global_load_ushort v64, v36, s[20:21]
	global_load_ushort v62, v37, s[20:21]
	global_load_ushort v60, v38, s[20:21]
	global_load_ushort v59, v39, s[20:21]
	global_load_ushort v57, v40, s[20:21]
	global_load_ushort v56, v41, s[20:21]
	global_load_ushort v55, v42, s[20:21]
	global_load_ushort v53, v43, s[20:21]
	v_add_u32_e32 v36, 0x18000, v34
	v_add_u32_e32 v37, 0x18040, v34
	v_add_u32_e32 v38, 0x18080, v34
	v_add_u32_e32 v39, 0x180c0, v34
	v_add_u32_e32 v43, 0x190c0, v34
	v_add_u32_e32 v40, 0x19000, v34
	v_add_u32_e32 v41, 0x19040, v34
	v_add_u32_e32 v42, 0x19080, v34
	global_load_ushort v54, v36, s[20:21]
	global_load_ushort v52, v37, s[20:21]
	global_load_ushort v50, v38, s[20:21]
	global_load_ushort v49, v39, s[20:21]
	global_load_ushort v48, v40, s[20:21]
	global_load_ushort v47, v41, s[20:21]
	global_load_ushort v45, v42, s[20:21]
	s_nop 0
	global_load_ushort v43, v43, s[20:21]
	v_add_u32_e32 v36, 0x1a000, v34
	v_add_u32_e32 v37, 0x1a040, v34
	v_add_u32_e32 v38, 0x1a080, v34
	v_add_u32_e32 v39, 0x1a0c0, v34
	v_add_u32_e32 v46, 0x1b000, v34
	v_add_u32_e32 v51, 0x1b040, v34
	v_add_u32_e32 v58, 0x1b080, v34
	v_add_u32_e32 v61, 0x1b0c0, v34
	global_load_ushort v44, v36, s[20:21]
	global_load_ushort v42, v37, s[20:21]
	global_load_ushort v41, v38, s[20:21]
	global_load_ushort v40, v39, s[20:21]
	s_nop 0
	global_load_ushort v39, v46, s[20:21]
	global_load_ushort v38, v51, s[20:21]
	global_load_ushort v37, v58, s[20:21]
	global_load_ushort v36, v61, s[20:21]
	s_waitcnt vmcnt(63) expcnt(7) lgkmcnt(15)
	s_barrier
; __device__ __forceinline__ void attn_unit_pp(int b, int h, int qb, int par, const bf16_t* __restrict__ QBp, const bf16_t* __restrict__ KBp, const bf16_t* __restrict__ VBp, ...
;     ...
;     for (int d0 = 0; d0 < 4; ++d0)
; #pragma unroll
;       for (int r = 0; r < 16; ++r) { const float v = o[d0][r] - lam * xs[(d0 * 16 + r) * 64]; o[d0][r] = v; ss[r] += v * v; }
; #pragma unroll
;     for (int r = 0; r < 16; ++r) { float s = ss[r];
; #pragma unroll
;       for (int x = 1; x < 32; x <<= 1) s += __builtin_bit_cast(float, __builtin_amdgcn_ds_bpermute((lane ^ x) << 2, __builtin_bit_cast(int, s)));
;       ss[r] = 1.0f / sqrtf(s * (1.0f / 128.0f) + 1e-5f); }
	ds_read2st64_b32 v[118:119], v78 offset1:1
	ds_read2st64_b32 v[144:145], v78 offset0:2 offset1:3
	ds_read2st64_b32 v[160:161], v78 offset0:4 offset1:5
	ds_read2st64_b32 v[172:173], v78 offset0:6 offset1:7
	s_waitcnt lgkmcnt(3)
	v_fma_f32 v198, -v175, v118, v9
	v_fma_f32 v194, -v175, v119, v13
	s_waitcnt lgkmcnt(2)
	v_fma_f32 v190, -v175, v144, v17
	v_fma_f32 v186, -v175, v145, v32
	s_waitcnt lgkmcnt(0)
	v_fma_f32 v150, -v175, v172, v82
	ds_read2st64_b32 v[118:119], v78 offset0:8 offset1:9
	v_fma_f32 v140, -v175, v173, v22
	ds_read2st64_b32 v[144:145], v78 offset0:10 offset1:11
	ds_read2st64_b32 v[172:173], v78 offset0:12 offset1:13
	ds_read2st64_b32 v[184:185], v78 offset0:14 offset1:15
	v_fma_f32 v171, -v175, v160, v67
	v_fma_f32 v161, -v175, v161, v80
	s_waitcnt lgkmcnt(3)
	v_fma_f32 v132, -v175, v118, v86
	v_fma_f32 v125, -v175, v119, v88
	s_waitcnt lgkmcnt(2)
	v_fma_f32 v116, -v175, v144, v90
	v_fma_f32 v107, -v175, v145, v91
	s_waitcnt lgkmcnt(1)
	v_fma_f32 v101, -v175, v172, v93
	v_fma_f32 v58, -v175, v173, v96
	s_waitcnt lgkmcnt(0)
	v_fma_f32 v51, -v175, v184, v98
	ds_read2st64_b32 v[118:119], v78 offset0:16 offset1:17
	v_fma_f32 v46, -v175, v185, v100
	ds_read2st64_b32 v[144:145], v78 offset0:18 offset1:19
	ds_read2st64_b32 v[172:173], v78 offset0:20 offset1:21
	ds_read2st64_b32 v[184:185], v78 offset0:22 offset1:23
	s_waitcnt vmcnt(62)
	v_lshlrev_b32_e32 v163, 16, v163
	v_mul_f32_e32 v163, 0xbfb8aa3b, v163
	s_waitcnt lgkmcnt(3)
	v_fma_f32 v202, -v175, v118, v6
	v_fma_f32 v199, -v175, v119, v10
	s_waitcnt lgkmcnt(0)
	v_fma_f32 v167, -v175, v184, v70
	v_fma_f32 v158, -v175, v185, v83
	ds_read2st64_b32 v[118:119], v78 offset0:24 offset1:25
	ds_read2st64_b32 v[184:185], v78 offset0:26 offset1:27
	ds_read2st64_b32 v[188:189], v78 offset0:28 offset1:29
	ds_read2st64_b32 v[192:193], v78 offset0:30 offset1:31
	v_fma_f32 v187, -v175, v172, v33
	v_fma_f32 v172, -v175, v173, v69
	s_waitcnt lgkmcnt(2)
	v_fma_f32 v135, -v175, v184, v87
	v_fma_f32 v155, -v175, v118, v84
	v_fma_f32 v127, -v175, v185, v89
	s_waitcnt lgkmcnt(1)
	v_fma_f32 v118, -v175, v188, v92
	v_fma_f32 v111, -v175, v189, v94
	s_waitcnt lgkmcnt(0)
	v_fma_f32 v103, -v175, v192, v97
	v_fma_f32 v61, -v175, v193, v99
	ds_read2st64_b32 v[184:185], v78 offset0:32 offset1:33
	ds_read2st64_b32 v[188:189], v78 offset0:34 offset1:35
	ds_read2st64_b32 v[192:193], v78 offset0:36 offset1:37
	ds_read2st64_b32 v[226:227], v78 offset0:38 offset1:39
	v_mul_f32_e32 v142, v202, v202
	v_fmac_f32_e32 v142, v198, v198
	s_waitcnt lgkmcnt(2)
	v_fma_f32 v205, -v175, v188, v11
	v_fma_f32 v209, -v175, v184, v4
	s_waitcnt lgkmcnt(0)
	v_fma_f32 v188, -v175, v226, v81
	v_fma_f32 v184, -v175, v227, v71
	ds_read2st64_b32 v[226:227], v78 offset0:40 offset1:41
	ds_read2st64_b32 v[228:229], v78 offset0:42 offset1:43
	ds_read2st64_b32 v[230:231], v78 offset0:44 offset1:45
	ds_read2st64_b32 v[232:233], v78 offset0:46 offset1:47
	v_fmac_f32_e32 v142, v209, v209
	v_fma_f32 v195, -v175, v144, v14
	v_fma_f32 v191, -v175, v145, v18
	s_waitcnt lgkmcnt(3)
	v_fma_f32 v173, -v175, v226, v72
	v_fma_f32 v164, -v175, v227, v73
	ds_read2st64_b32 v[226:227], v78 offset0:48 offset1:49
	v_fma_f32 v145, -v175, v119, v85
	s_waitcnt lgkmcnt(3)
	v_fma_f32 v156, -v175, v228, v74
	v_fma_f32 v146, -v175, v229, v75
	s_waitcnt lgkmcnt(2)
	v_fma_f32 v136, -v175, v230, v76
	s_waitcnt lgkmcnt(0)
	v_fma_f32 v212, -v175, v226, v0
	v_fmac_f32_e32 v142, v212, v212
	v_fma_f32 v128, -v175, v231, v77
	v_fma_f32 v119, -v175, v232, v95
	v_fma_f32 v112, -v175, v233, v79
	ds_read2st64_b32 v[228:229], v78 offset0:50 offset1:51
	ds_read2st64_b32 v[230:231], v78 offset0:52 offset1:53
	ds_read2st64_b32 v[232:233], v78 offset0:54 offset1:55
	s_waitcnt lgkmcnt(0)
	s_nop 1
	v_add_f32_dpp v142, v142, v142 quad_perm:[1,0,3,2] row_mask:0xf bank_mask:0xf
	v_mul_f32_e32 v215, v199, v199
	v_fma_f32 v210, -v175, v227, v5
	ds_read2st64_b32 v[226:227], v78 offset0:56 offset1:57
	v_fmac_f32_e32 v215, v194, v194
	s_waitcnt lgkmcnt(0)
	s_nop 1
	v_add_f32_dpp v142, v142, v142 quad_perm:[2,3,0,1] row_mask:0xf bank_mask:0xf
	v_fma_f32 v207, -v175, v185, v7
	v_fma_f32 v208, -v175, v228, v8
	v_fma_f32 v206, -v175, v229, v12
	v_fma_f32 v204, -v175, v230, v16
	s_waitcnt lgkmcnt(0)
	s_nop 1
	v_add_f32_dpp v142, v142, v142 row_half_mirror row_mask:0xf bank_mask:0xf
	v_fma_f32 v203, -v175, v231, v20
	v_fma_f32 v200, -v175, v232, v21
	v_fma_f32 v196, -v175, v233, v23
	ds_read2st64_b32 v[228:229], v78 offset0:58 offset1:59
	ds_read2st64_b32 v[230:231], v78 offset0:60 offset1:61
	ds_read2st64_b32 v[232:233], v78 offset0:62 offset1:63
	s_waitcnt lgkmcnt(0)
	s_nop 1
	v_add_f32_dpp v142, v142, v142 row_mirror row_mask:0xf bank_mask:0xf
	v_fmac_f32_e32 v215, v207, v207
	v_fmac_f32_e32 v215, v210, v210
	s_waitcnt lgkmcnt(0)
	v_fma_f32 v170, -v175, v229, v27
	s_waitcnt lgkmcnt(0)
	v_mov_b32_e32 v144, v142
	s_nop 1
	v_permlane16_swap_b32_e32 v142, v144
	v_add_f32_e32 v142, v142, v144
	v_fmamk_f32 v142, v142, 0x3c000000, v177
	v_mul_f32_e32 v144, 0x4f800000, v142
	v_cmp_gt_f32_e32 vcc, s49, v142
	v_fma_f32 v197, -v175, v192, v19
	v_fma_f32 v192, -v175, v193, v66
	v_cndmask_b32_e32 v144, v142, v144, vcc
	v_fma_f32 v193, -v175, v226, v24
	v_sqrt_f32_e32 v226, v144
	v_fma_f32 v201, -v175, v189, v15
	v_fma_f32 v189, -v175, v227, v25
	s_waitcnt lgkmcnt(0)
	s_nop 1
	v_add_f32_dpp v215, v215, v215 quad_perm:[1,0,3,2] row_mask:0xf bank_mask:0xf
	v_add_u32_e32 v227, -1, v226
	v_fma_f32 v185, -v175, v228, v26
	v_fma_f32 v228, -v227, v226, v144
	v_cmp_ge_f32_e64 s[0:1], 0, v228
	v_add_u32_e32 v228, 1, v226
	v_mul_f32_e32 v216, v195, v195
	v_cndmask_b32_e64 v227, v226, v227, s[0:1]
	v_fma_f32 v226, -v228, v226, v144
	v_cmp_lt_f32_e64 s[0:1], 0, v226
	s_waitcnt lgkmcnt(0)
; __device__ __forceinline__ void attn_unit_pp(int b, int h, int qb, int par, const bf16_t* __restrict__ QBp, const bf16_t* __restrict__ KBp, const bf16_t* __restrict__ VBp, ...
;     ...
;     for (int r = 0; r < 16; ++r) { float s = ss[r];
; #pragma unroll
;       for (int x = 1; x < 32; x <<= 1) s += __builtin_bit_cast(float, __builtin_amdgcn_ds_bpermute((lane ^ x) << 2, __builtin_bit_cast(int, s)));
;       ss[r] = 1.0f / sqrtf(s * (1.0f / 128.0f) + 1e-5f); }
	s_nop 1
	v_add_f32_dpp v215, v215, v215 quad_perm:[2,3,0,1] row_mask:0xf bank_mask:0xf
	v_fmac_f32_e32 v216, v190, v190
	v_cndmask_b32_e64 v226, v227, v228, s[0:1]
	v_mul_f32_e32 v227, 0x37800000, v226
	v_cndmask_b32_e32 v226, v226, v227, vcc
	v_cmp_class_f32_e32 vcc, v144, v176
	v_fmac_f32_e32 v216, v205, v205
	v_fmac_f32_e32 v216, v208, v208
	v_cndmask_b32_e32 v226, v226, v144, vcc
	s_waitcnt lgkmcnt(0)
	s_nop 1
	v_add_f32_dpp v215, v215, v215 row_half_mirror row_mask:0xf bank_mask:0xf
	v_div_scale_f32 v228, s[0:1], v226, v226, 1.0
	v_rcp_f32_e32 v229, v228
	v_fma_f32 v160, -v175, v230, v28
	s_waitcnt lgkmcnt(0)
	s_nop 1
	v_add_f32_dpp v215, v215, v215 row_mirror row_mask:0xf bank_mask:0xf
	v_fma_f32 v144, -v175, v233, v31
	v_fma_f32 v230, -v228, v229, 1.0
	v_fmac_f32_e32 v229, v230, v229
	s_waitcnt lgkmcnt(0)
	v_mov_b32_e32 v227, v215
	s_nop 1
	v_permlane16_swap_b32_e32 v215, v227
	v_add_f32_e32 v215, v215, v227
	v_fmamk_f32 v215, v215, 0x3c000000, v177
	v_mul_f32_e32 v227, 0x4f800000, v215
	v_cmp_gt_f32_e64 s[0:1], s49, v215
	v_div_scale_f32 v230, vcc, 1.0, v226, 1.0
	s_nop 0
	v_cndmask_b32_e64 v215, v215, v227, s[0:1]
	v_sqrt_f32_e32 v227, v215
	v_fma_f32 v153, -v175, v231, v29
	v_mul_f32_e32 v231, v230, v229
	v_fma_f32 v142, -v175, v232, v30
	v_fma_f32 v232, -v228, v231, v230
	v_fmac_f32_e32 v231, v232, v229
	v_fma_f32 v228, -v228, v231, v230
	v_add_u32_e32 v230, -1, v227
	s_waitcnt lgkmcnt(0)
	s_nop 1
	v_add_f32_dpp v216, v216, v216 quad_perm:[1,0,3,2] row_mask:0xf bank_mask:0xf
	v_fma_f32 v232, -v230, v227, v215
	v_cmp_ge_f32_e64 s[2:3], 0, v232
	v_add_u32_e32 v232, 1, v227
	v_mul_f32_e32 v218, v191, v191
	v_cndmask_b32_e64 v230, v227, v230, s[2:3]
	v_fma_f32 v227, -v232, v227, v215
	v_cmp_lt_f32_e64 s[2:3], 0, v227
	s_waitcnt lgkmcnt(0)
	s_nop 1
	v_add_f32_dpp v216, v216, v216 quad_perm:[2,3,0,1] row_mask:0xf bank_mask:0xf
	v_fmac_f32_e32 v218, v186, v186
	v_cndmask_b32_e64 v227, v230, v232, s[2:3]
	v_mul_f32_e32 v230, 0x37800000, v227
	v_cndmask_b32_e64 v227, v227, v230, s[0:1]
	v_cmp_class_f32_e64 s[0:1], v215, v176
	v_fmac_f32_e32 v218, v201, v201
	v_fmac_f32_e32 v218, v206, v206
	v_cndmask_b32_e64 v227, v227, v215, s[0:1]
	s_waitcnt lgkmcnt(0)
	s_nop 1
	v_add_f32_dpp v216, v216, v216 row_half_mirror row_mask:0xf bank_mask:0xf
	v_div_scale_f32 v232, s[0:1], v227, v227, 1.0
	v_rcp_f32_e32 v233, v232
	v_div_fmas_f32 v215, v228, v229, v231
	s_waitcnt lgkmcnt(0)
	s_nop 1
	v_add_f32_dpp v216, v216, v216 row_mirror row_mask:0xf bank_mask:0xf
	v_div_fixup_f32 v215, v215, v226, 1.0
	v_fma_f32 v226, -v232, v233, 1.0
	v_fmac_f32_e32 v233, v226, v233
	v_div_scale_f32 v226, vcc, 1.0, v227, 1.0
	v_mul_f32_e32 v229, v226, v233
	s_waitcnt lgkmcnt(0)
	v_mov_b32_e32 v228, v216
	s_nop 1
	v_permlane16_swap_b32_e32 v216, v228
	v_add_f32_e32 v216, v216, v228
	v_fmamk_f32 v216, v216, 0x3c000000, v177
	v_fma_f32 v230, -v232, v229, v226
	v_mul_f32_e32 v228, 0x4f800000, v216
	v_cmp_gt_f32_e64 s[0:1], s49, v216
	v_fmac_f32_e32 v229, v230, v233
	v_fma_f32 v226, -v232, v229, v226
	v_cndmask_b32_e64 v216, v216, v228, s[0:1]
	v_sqrt_f32_e32 v228, v216
	v_mul_f32_e32 v234, v187, v187
	v_fmac_f32_e32 v234, v171, v171
	v_fmac_f32_e32 v234, v197, v197
	v_add_u32_e32 v230, -1, v228
	s_waitcnt lgkmcnt(0)
	s_nop 1
	v_add_f32_dpp v218, v218, v218 quad_perm:[1,0,3,2] row_mask:0xf bank_mask:0xf
	v_fma_f32 v231, -v230, v228, v216
	v_cmp_ge_f32_e64 s[2:3], 0, v231
	v_add_u32_e32 v231, 1, v228
	v_fmac_f32_e32 v234, v204, v204
	v_cndmask_b32_e64 v230, v228, v230, s[2:3]
	v_fma_f32 v228, -v231, v228, v216
	v_cmp_lt_f32_e64 s[2:3], 0, v228
	s_waitcnt lgkmcnt(0)
	s_nop 1
	v_add_f32_dpp v218, v218, v218 quad_perm:[2,3,0,1] row_mask:0xf bank_mask:0xf
	v_mul_f32_e32 v219, v172, v172
	v_cndmask_b32_e64 v228, v230, v231, s[2:3]
	v_mul_f32_e32 v230, 0x37800000, v228
	v_cndmask_b32_e64 v228, v228, v230, s[0:1]
	v_cmp_class_f32_e64 s[0:1], v216, v176
	v_fmac_f32_e32 v219, v161, v161
	v_fmac_f32_e32 v219, v192, v192
	v_cndmask_b32_e64 v228, v228, v216, s[0:1]
	s_waitcnt lgkmcnt(0)
	s_nop 1
	v_add_f32_dpp v218, v218, v218 row_half_mirror row_mask:0xf bank_mask:0xf
	v_div_fmas_f32 v216, v226, v233, v229
	v_div_fixup_f32 v216, v216, v227, 1.0
	v_div_scale_f32 v231, s[0:1], v228, v228, 1.0
	s_waitcnt lgkmcnt(0)
	s_nop 1
	v_add_f32_dpp v218, v218, v218 row_mirror row_mask:0xf bank_mask:0xf
	v_rcp_f32_e32 v232, v231
	v_fmac_f32_e32 v219, v203, v203
	v_mul_f32_e32 v221, v167, v167
	s_waitcnt lgkmcnt(0)
	v_mov_b32_e32 v227, v218
	s_nop 1
	v_permlane16_swap_b32_e32 v218, v227
	v_add_f32_e32 v218, v218, v227
	v_fmamk_f32 v218, v218, 0x3c000000, v177
	v_mul_f32_e32 v227, 0x4f800000, v218
	v_cmp_gt_f32_e64 s[0:1], s49, v218
	v_fma_f32 v226, -v231, v232, 1.0
	v_fmac_f32_e32 v232, v226, v232
	v_cndmask_b32_e64 v218, v218, v227, s[0:1]
	v_sqrt_f32_e32 v227, v218
	v_div_scale_f32 v226, vcc, 1.0, v228, 1.0
	v_mul_f32_e32 v229, v226, v232
	v_fma_f32 v230, -v231, v229, v226
	v_fmac_f32_e32 v229, v230, v232
	v_add_u32_e32 v230, -1, v227
	v_fma_f32 v226, -v231, v229, v226
	v_fma_f32 v231, -v230, v227, v218
	s_waitcnt lgkmcnt(0)
	s_nop 1
	v_add_f32_dpp v233, v234, v234 quad_perm:[1,0,3,2] row_mask:0xf bank_mask:0xf
	v_cmp_ge_f32_e64 s[2:3], 0, v231
	v_add_u32_e32 v231, 1, v227
	v_cndmask_b32_e64 v230, v227, v230, s[2:3]
	v_fma_f32 v227, -v231, v227, v218
	v_cmp_lt_f32_e64 s[2:3], 0, v227
	v_fmac_f32_e32 v221, v150, v150
	v_fmac_f32_e32 v221, v188, v188
	v_cndmask_b32_e64 v227, v230, v231, s[2:3]
	v_mul_f32_e32 v230, 0x37800000, v227
	v_cndmask_b32_e64 v227, v227, v230, s[0:1]
	s_waitcnt lgkmcnt(0)
; __device__ __forceinline__ void attn_unit_pp(int b, int h, int qb, int par, const bf16_t* __restrict__ QBp, const bf16_t* __restrict__ KBp, const bf16_t* __restrict__ VBp, ...
;     ...
;     for (int r = 0; r < 16; ++r) { float s = ss[r];
; #pragma unroll
;       for (int x = 1; x < 32; x <<= 1) s += __builtin_bit_cast(float, __builtin_amdgcn_ds_bpermute((lane ^ x) << 2, __builtin_bit_cast(int, s)));
;       ss[r] = 1.0f / sqrtf(s * (1.0f / 128.0f) + 1e-5f); }
	s_nop 1
	v_add_f32_dpp v230, v233, v233 quad_perm:[2,3,0,1] row_mask:0xf bank_mask:0xf
	v_cmp_class_f32_e64 s[0:1], v218, v176
	v_fmac_f32_e32 v221, v200, v200
	v_mul_f32_e32 v222, v158, v158
	v_cndmask_b32_e64 v227, v227, v218, s[0:1]
	s_waitcnt lgkmcnt(0)
	s_nop 1
	v_add_f32_dpp v230, v230, v230 row_half_mirror row_mask:0xf bank_mask:0xf
	v_div_scale_f32 v233, s[0:1], v227, v227, 1.0
	v_div_fmas_f32 v218, v226, v232, v229
	v_rcp_f32_e32 v234, v233
	v_div_fixup_f32 v218, v218, v228, 1.0
	s_waitcnt lgkmcnt(0)
	s_nop 1
	v_add_f32_dpp v228, v230, v230 row_mirror row_mask:0xf bank_mask:0xf
	v_fma_f32 v226, -v233, v234, 1.0
	v_fmac_f32_e32 v234, v226, v234
	v_div_scale_f32 v226, vcc, 1.0, v227, 1.0
	v_mul_f32_e32 v230, v226, v234
	s_waitcnt lgkmcnt(0)
	v_mov_b32_e32 v229, v228
	s_nop 1
	v_permlane16_swap_b32_e32 v228, v229
	v_add_f32_e32 v228, v228, v229
	v_fmamk_f32 v228, v228, 0x3c000000, v177
	v_fma_f32 v231, -v233, v230, v226
	v_mul_f32_e32 v229, 0x4f800000, v228
	v_cmp_gt_f32_e64 s[0:1], s49, v228
	v_fmac_f32_e32 v230, v231, v234
	v_fma_f32 v226, -v233, v230, v226
	v_cndmask_b32_e64 v228, v228, v229, s[0:1]
	v_sqrt_f32_e32 v229, v228
	v_fmac_f32_e32 v222, v140, v140
	v_fmac_f32_e32 v222, v184, v184
	v_fmac_f32_e32 v222, v196, v196
	v_add_u32_e32 v231, -1, v229
	s_waitcnt lgkmcnt(0)
	s_nop 1
	v_add_f32_dpp v219, v219, v219 quad_perm:[1,0,3,2] row_mask:0xf bank_mask:0xf
	v_fma_f32 v232, -v231, v229, v228
	v_cmp_ge_f32_e64 s[2:3], 0, v232
	v_add_u32_e32 v232, 1, v229
	v_mul_f32_e32 v223, v155, v155
	v_cndmask_b32_e64 v231, v229, v231, s[2:3]
	v_fma_f32 v229, -v232, v229, v228
	v_cmp_lt_f32_e64 s[2:3], 0, v229
	s_waitcnt lgkmcnt(0)
	s_nop 1
	v_add_f32_dpp v219, v219, v219 quad_perm:[2,3,0,1] row_mask:0xf bank_mask:0xf
	v_fmac_f32_e32 v223, v132, v132
	v_cndmask_b32_e64 v229, v231, v232, s[2:3]
	v_mul_f32_e32 v231, 0x37800000, v229
	v_cndmask_b32_e64 v229, v229, v231, s[0:1]
	v_cmp_class_f32_e64 s[0:1], v228, v176
	v_fmac_f32_e32 v223, v173, v173
	v_fmac_f32_e32 v223, v193, v193
	v_cndmask_b32_e64 v228, v229, v228, s[0:1]
	s_waitcnt lgkmcnt(0)
	s_nop 1
	v_add_f32_dpp v231, v219, v219 row_half_mirror row_mask:0xf bank_mask:0xf
	v_div_fmas_f32 v219, v226, v234, v230
	v_div_fixup_f32 v219, v219, v227, 1.0
	v_div_scale_f32 v229, s[0:1], v228, v228, 1.0
	s_waitcnt lgkmcnt(0)
	s_nop 1
	v_add_f32_dpp v227, v231, v231 row_mirror row_mask:0xf bank_mask:0xf
	v_rcp_f32_e32 v232, v229
	v_mul_f32_e32 v225, v145, v145
	v_fmac_f32_e32 v225, v125, v125
	s_waitcnt lgkmcnt(0)
	v_mov_b32_e32 v230, v227
	s_nop 1
	v_permlane16_swap_b32_e32 v227, v230
	v_add_f32_e32 v227, v227, v230
	v_fmamk_f32 v227, v227, 0x3c000000, v177
	v_mul_f32_e32 v230, 0x4f800000, v227
	v_cmp_gt_f32_e64 s[0:1], s49, v227
	v_fma_f32 v226, -v229, v232, 1.0
	v_fmac_f32_e32 v232, v226, v232
	v_cndmask_b32_e64 v227, v227, v230, s[0:1]
	v_div_scale_f32 v226, vcc, 1.0, v228, 1.0
	v_sqrt_f32_e32 v230, v227
	v_mul_f32_e32 v231, v226, v232
	v_fma_f32 v233, -v229, v231, v226
	v_fmac_f32_e32 v231, v233, v232
	v_fma_f32 v226, -v229, v231, v226
	v_add_u32_e32 v229, -1, v230
	s_waitcnt lgkmcnt(0)
	s_nop 1
	v_add_f32_dpp v221, v221, v221 quad_perm:[1,0,3,2] row_mask:0xf bank_mask:0xf
	v_fma_f32 v233, -v229, v230, v227
	v_cmp_ge_f32_e64 s[2:3], 0, v233
	v_add_u32_e32 v233, 1, v230
	v_fmac_f32_e32 v225, v164, v164
	v_cndmask_b32_e64 v229, v230, v229, s[2:3]
	v_fma_f32 v230, -v233, v230, v227
	v_cmp_lt_f32_e64 s[2:3], 0, v230
	s_waitcnt lgkmcnt(0)
	s_nop 1
	v_add_f32_dpp v221, v221, v221 quad_perm:[2,3,0,1] row_mask:0xf bank_mask:0xf
	v_fmac_f32_e32 v225, v189, v189
	v_cndmask_b32_e64 v229, v229, v233, s[2:3]
	v_mul_f32_e32 v230, 0x37800000, v229
	v_cndmask_b32_e64 v229, v229, v230, s[0:1]
	v_cmp_class_f32_e64 s[0:1], v227, v176
	v_mul_f32_e32 v224, v135, v135
	v_fmac_f32_e32 v224, v116, v116
	v_cndmask_b32_e64 v227, v229, v227, s[0:1]
	s_waitcnt lgkmcnt(0)
	s_nop 1
	v_add_f32_dpp v230, v221, v221 row_half_mirror row_mask:0xf bank_mask:0xf
	v_div_fmas_f32 v221, v226, v232, v231
	v_div_fixup_f32 v221, v221, v228, 1.0
	v_div_scale_f32 v229, s[0:1], v227, v227, 1.0
	s_waitcnt lgkmcnt(0)
	s_nop 1
	v_add_f32_dpp v228, v230, v230 row_mirror row_mask:0xf bank_mask:0xf
	v_rcp_f32_e32 v233, v229
	v_fmac_f32_e32 v224, v156, v156
	v_fmac_f32_e32 v224, v185, v185
	s_waitcnt lgkmcnt(0)
	v_mov_b32_e32 v230, v228
	s_nop 1
	v_permlane16_swap_b32_e32 v228, v230
	v_add_f32_e32 v228, v228, v230
	v_fmamk_f32 v228, v228, 0x3c000000, v177
	v_mul_f32_e32 v230, 0x4f800000, v228
	v_cmp_gt_f32_e64 s[0:1], s49, v228
	v_fma_f32 v226, -v229, v233, 1.0
	v_fmac_f32_e32 v233, v226, v233
	v_cndmask_b32_e64 v228, v228, v230, s[0:1]
	v_div_scale_f32 v226, vcc, 1.0, v227, 1.0
	v_sqrt_f32_e32 v230, v228
	v_mul_f32_e32 v231, v226, v233
	v_fma_f32 v232, -v229, v231, v226
	v_fmac_f32_e32 v231, v232, v233
	v_fma_f32 v226, -v229, v231, v226
	v_add_u32_e32 v229, -1, v230
	s_waitcnt lgkmcnt(0)
	s_nop 1
	v_add_f32_dpp v222, v222, v222 quad_perm:[1,0,3,2] row_mask:0xf bank_mask:0xf
	v_fma_f32 v232, -v229, v230, v228
	v_cmp_ge_f32_e64 s[2:3], 0, v232
	v_add_u32_e32 v232, 1, v230
	v_mul_f32_e32 v220, v127, v127
	v_cndmask_b32_e64 v229, v230, v229, s[2:3]
	v_fma_f32 v230, -v232, v230, v228
	v_cmp_lt_f32_e64 s[2:3], 0, v230
	s_waitcnt lgkmcnt(0)
	s_nop 1
	v_add_f32_dpp v222, v222, v222 quad_perm:[2,3,0,1] row_mask:0xf bank_mask:0xf
	v_fmac_f32_e32 v220, v107, v107
	v_cndmask_b32_e64 v229, v229, v232, s[2:3]
	v_mul_f32_e32 v230, 0x37800000, v229
	v_cndmask_b32_e64 v229, v229, v230, s[0:1]
	v_cmp_class_f32_e64 s[0:1], v228, v176
	v_fmac_f32_e32 v220, v146, v146
	v_fmac_f32_e32 v220, v170, v170
	v_cndmask_b32_e64 v228, v229, v228, s[0:1]
	s_waitcnt lgkmcnt(0)
; __device__ __forceinline__ void attn_unit_pp(int b, int h, int qb, int par, const bf16_t* __restrict__ QBp, const bf16_t* __restrict__ KBp, const bf16_t* __restrict__ VBp, ...
;     ...
;     for (int r = 0; r < 16; ++r) { float s = ss[r];
; #pragma unroll
;       for (int x = 1; x < 32; x <<= 1) s += __builtin_bit_cast(float, __builtin_amdgcn_ds_bpermute((lane ^ x) << 2, __builtin_bit_cast(int, s)));
;       ss[r] = 1.0f / sqrtf(s * (1.0f / 128.0f) + 1e-5f); }
	s_nop 1
	v_add_f32_dpp v230, v222, v222 row_half_mirror row_mask:0xf bank_mask:0xf
	v_div_fmas_f32 v222, v226, v233, v231
	v_div_fixup_f32 v222, v222, v227, 1.0
	v_div_scale_f32 v229, s[0:1], v228, v228, 1.0
	s_waitcnt lgkmcnt(0)
	s_nop 1
	v_add_f32_dpp v227, v230, v230 row_mirror row_mask:0xf bank_mask:0xf
	v_rcp_f32_e32 v232, v229
	v_mul_f32_e32 v217, v118, v118
	v_fmac_f32_e32 v217, v101, v101
	s_waitcnt lgkmcnt(0)
	v_mov_b32_e32 v230, v227
	s_nop 1
	v_permlane16_swap_b32_e32 v227, v230
	v_add_f32_e32 v227, v227, v230
	v_fmamk_f32 v227, v227, 0x3c000000, v177
	v_mul_f32_e32 v230, 0x4f800000, v227
	v_cmp_gt_f32_e64 s[0:1], s49, v227
	v_fma_f32 v226, -v229, v232, 1.0
	v_fmac_f32_e32 v232, v226, v232
	v_cndmask_b32_e64 v227, v227, v230, s[0:1]
	v_div_scale_f32 v226, vcc, 1.0, v228, 1.0
	v_sqrt_f32_e32 v230, v227
	v_mul_f32_e32 v231, v226, v232
	v_fma_f32 v233, -v229, v231, v226
	v_fmac_f32_e32 v231, v233, v232
	v_fma_f32 v226, -v229, v231, v226
	v_add_u32_e32 v229, -1, v230
	s_waitcnt lgkmcnt(0)
	s_nop 1
	v_add_f32_dpp v223, v223, v223 quad_perm:[1,0,3,2] row_mask:0xf bank_mask:0xf
	v_fma_f32 v233, -v229, v230, v227
	v_cmp_ge_f32_e64 s[2:3], 0, v233
	v_add_u32_e32 v233, 1, v230
	v_fmac_f32_e32 v217, v136, v136
	v_cndmask_b32_e64 v229, v230, v229, s[2:3]
	v_fma_f32 v230, -v233, v230, v227
	v_cmp_lt_f32_e64 s[2:3], 0, v230
	s_waitcnt lgkmcnt(0)
	s_nop 1
	v_add_f32_dpp v223, v223, v223 quad_perm:[2,3,0,1] row_mask:0xf bank_mask:0xf
	v_fmac_f32_e32 v217, v160, v160
	v_cndmask_b32_e64 v229, v229, v233, s[2:3]
	v_mul_f32_e32 v230, 0x37800000, v229
	v_cndmask_b32_e64 v229, v229, v230, s[0:1]
	v_cmp_class_f32_e64 s[0:1], v227, v176
	v_mul_f32_e32 v214, v111, v111
	v_fmac_f32_e32 v214, v58, v58
	v_cndmask_b32_e64 v227, v229, v227, s[0:1]
	s_waitcnt lgkmcnt(0)
	s_nop 1
	v_add_f32_dpp v230, v223, v223 row_half_mirror row_mask:0xf bank_mask:0xf
	v_div_fmas_f32 v223, v226, v232, v231
	v_div_fixup_f32 v223, v223, v228, 1.0
	v_div_scale_f32 v229, s[0:1], v227, v227, 1.0
	s_waitcnt lgkmcnt(0)
	s_nop 1
	v_add_f32_dpp v228, v230, v230 row_mirror row_mask:0xf bank_mask:0xf
	v_rcp_f32_e32 v233, v229
	v_fmac_f32_e32 v214, v128, v128
	v_fmac_f32_e32 v214, v153, v153
	s_waitcnt lgkmcnt(0)
	v_mov_b32_e32 v230, v228
	s_nop 1
	v_permlane16_swap_b32_e32 v228, v230
	v_add_f32_e32 v228, v228, v230
	v_fmamk_f32 v228, v228, 0x3c000000, v177
	v_mul_f32_e32 v230, 0x4f800000, v228
	v_cmp_gt_f32_e64 s[0:1], s49, v228
	v_fma_f32 v226, -v229, v233, 1.0
	v_fmac_f32_e32 v233, v226, v233
	v_cndmask_b32_e64 v228, v228, v230, s[0:1]
	v_div_scale_f32 v226, vcc, 1.0, v227, 1.0
	v_sqrt_f32_e32 v230, v228
	v_mul_f32_e32 v231, v226, v233
	v_fma_f32 v232, -v229, v231, v226
	v_fmac_f32_e32 v231, v232, v233
	v_fma_f32 v226, -v229, v231, v226
	v_add_u32_e32 v229, -1, v230
	s_waitcnt lgkmcnt(0)
	s_nop 1
	v_add_f32_dpp v225, v225, v225 quad_perm:[1,0,3,2] row_mask:0xf bank_mask:0xf
	v_fma_f32 v232, -v229, v230, v228
	v_cmp_ge_f32_e64 s[2:3], 0, v232
	v_add_u32_e32 v232, 1, v230
	v_mul_f32_e32 v213, v103, v103
	v_cndmask_b32_e64 v229, v230, v229, s[2:3]
	v_fma_f32 v230, -v232, v230, v228
	v_cmp_lt_f32_e64 s[2:3], 0, v230
	s_waitcnt lgkmcnt(0)
	s_nop 1
	v_add_f32_dpp v225, v225, v225 quad_perm:[2,3,0,1] row_mask:0xf bank_mask:0xf
	v_fmac_f32_e32 v213, v51, v51
	v_cndmask_b32_e64 v229, v229, v232, s[2:3]
	v_mul_f32_e32 v230, 0x37800000, v229
	v_cndmask_b32_e64 v229, v229, v230, s[0:1]
	v_cmp_class_f32_e64 s[0:1], v228, v176
	v_fmac_f32_e32 v213, v119, v119
	v_fmac_f32_e32 v213, v142, v142
	v_cndmask_b32_e64 v228, v229, v228, s[0:1]
	s_waitcnt lgkmcnt(0)
	s_nop 1
	v_add_f32_dpp v230, v225, v225 row_half_mirror row_mask:0xf bank_mask:0xf
	v_div_fmas_f32 v225, v226, v233, v231
	v_div_fixup_f32 v225, v225, v227, 1.0
	v_div_scale_f32 v229, s[0:1], v228, v228, 1.0
	s_waitcnt lgkmcnt(0)
	s_nop 1
	v_add_f32_dpp v227, v230, v230 row_mirror row_mask:0xf bank_mask:0xf
	v_rcp_f32_e32 v232, v229
	v_mul_f32_e32 v211, v61, v61
	v_fmac_f32_e32 v211, v46, v46
	s_waitcnt lgkmcnt(0)
	v_mov_b32_e32 v230, v227
	s_nop 1
	v_permlane16_swap_b32_e32 v227, v230
	v_add_f32_e32 v227, v227, v230
	v_fmamk_f32 v227, v227, 0x3c000000, v177
	v_mul_f32_e32 v230, 0x4f800000, v227
	v_cmp_gt_f32_e64 s[0:1], s49, v227
	v_fma_f32 v226, -v229, v232, 1.0
	v_fmac_f32_e32 v232, v226, v232
	v_cndmask_b32_e64 v227, v227, v230, s[0:1]
	v_div_scale_f32 v226, vcc, 1.0, v228, 1.0
	v_sqrt_f32_e32 v230, v227
	v_mul_f32_e32 v231, v226, v232
	v_fma_f32 v233, -v229, v231, v226
	v_fmac_f32_e32 v231, v233, v232
	v_fma_f32 v226, -v229, v231, v226
	v_add_u32_e32 v229, -1, v230
	s_waitcnt lgkmcnt(0)
	s_nop 1
	v_add_f32_dpp v224, v224, v224 quad_perm:[1,0,3,2] row_mask:0xf bank_mask:0xf
	v_fma_f32 v233, -v229, v230, v227
	v_cmp_ge_f32_e64 s[2:3], 0, v233
	v_add_u32_e32 v233, 1, v230
	v_fmac_f32_e32 v211, v112, v112
	v_cndmask_b32_e64 v229, v230, v229, s[2:3]
	v_fma_f32 v230, -v233, v230, v227
	v_cmp_lt_f32_e64 s[2:3], 0, v230
	s_waitcnt lgkmcnt(0)
	s_nop 1
	v_add_f32_dpp v224, v224, v224 quad_perm:[2,3,0,1] row_mask:0xf bank_mask:0xf
	v_fmac_f32_e32 v211, v144, v144
	v_cndmask_b32_e64 v229, v229, v233, s[2:3]
	v_mul_f32_e32 v230, 0x37800000, v229
	v_cndmask_b32_e64 v229, v229, v230, s[0:1]
	v_cmp_class_f32_e64 s[0:1], v227, v176
	s_waitcnt vmcnt(61)
	v_lshlrev_b32_e32 v162, 16, v162
	v_exp_f32_e32 v163, v163
	v_cndmask_b32_e64 v227, v229, v227, s[0:1]
	s_waitcnt lgkmcnt(0)
	s_nop 1
	v_add_f32_dpp v230, v224, v224 row_half_mirror row_mask:0xf bank_mask:0xf
	v_div_fmas_f32 v224, v226, v232, v231
	v_div_fixup_f32 v224, v224, v228, 1.0
	v_div_scale_f32 v229, s[0:1], v227, v227, 1.0
	s_waitcnt lgkmcnt(0)
; __device__ __forceinline__ float sigm_(float x) { return __builtin_amdgcn_rcpf(1.0f + __builtin_amdgcn_exp2f(-1.4426950408889634f * x)); }
; __device__ __forceinline__ void attn_unit_pp(int b, int h, int qb, int par, const bf16_t* __restrict__ QBp, const bf16_t* __restrict__ KBp, const bf16_t* __restrict__ VBp, ...
;     ...
;     for (int r = 0; r < 16; ++r) { float s = ss[r];
; #pragma unroll
;       for (int x = 1; x < 32; x <<= 1) s += __builtin_bit_cast(float, __builtin_amdgcn_ds_bpermute((lane ^ x) << 2, __builtin_bit_cast(int, s)));
;       ss[r] = 1.0f / sqrtf(s * (1.0f / 128.0f) + 1e-5f); }
;     float sg[4];
; #pragma unroll
;     for (int d0 = 0; d0 < 4; ++d0) sg[d0] = sub_g[d0 * 32 + r32] * 0.8f;
; #pragma unroll
;     for (int r = 0; r < 16; ++r)
; #pragma unroll
;       for (int d0 = 0; d0 < 4; ++d0) { const float ga = __uint_as_float(gate16[r * 4 + d0] << 16); o[d0][r] = o[d0][r] * ss[r] * sg[d0] * sigm_(ga); }
	s_nop 1
	v_add_f32_dpp v228, v230, v230 row_mirror row_mask:0xf bank_mask:0xf
	v_rcp_f32_e32 v233, v229
	v_mul_f32_e32 v162, 0xbfb8aa3b, v162
	s_waitcnt vmcnt(60)
	v_lshlrev_b32_e32 v159, 16, v159
	s_waitcnt lgkmcnt(0)
	v_mov_b32_e32 v230, v228
	s_nop 1
	v_permlane16_swap_b32_e32 v228, v230
	v_add_f32_e32 v228, v228, v230
	v_fmamk_f32 v228, v228, 0x3c000000, v177
	v_mul_f32_e32 v230, 0x4f800000, v228
	v_cmp_gt_f32_e64 s[0:1], s49, v228
	v_fma_f32 v226, -v229, v233, 1.0
	v_fmac_f32_e32 v233, v226, v233
	v_cndmask_b32_e64 v228, v228, v230, s[0:1]
	v_div_scale_f32 v226, vcc, 1.0, v227, 1.0
	v_sqrt_f32_e32 v230, v228
	v_mul_f32_e32 v231, v226, v233
	v_fma_f32 v232, -v229, v231, v226
	v_fmac_f32_e32 v231, v232, v233
	v_fma_f32 v226, -v229, v231, v226
	v_add_u32_e32 v229, -1, v230
	s_waitcnt lgkmcnt(0)
	s_nop 1
	v_add_f32_dpp v220, v220, v220 quad_perm:[1,0,3,2] row_mask:0xf bank_mask:0xf
	v_fma_f32 v232, -v229, v230, v228
	v_cmp_ge_f32_e64 s[2:3], 0, v232
	v_add_u32_e32 v232, 1, v230
	v_add_f32_e32 v163, 1.0, v163
	v_cndmask_b32_e64 v229, v230, v229, s[2:3]
	v_fma_f32 v230, -v232, v230, v228
	v_cmp_lt_f32_e64 s[2:3], 0, v230
	s_waitcnt lgkmcnt(0)
	s_nop 1
	v_add_f32_dpp v220, v220, v220 quad_perm:[2,3,0,1] row_mask:0xf bank_mask:0xf
	v_mul_f32_e32 v159, 0xbfb8aa3b, v159
	v_cndmask_b32_e64 v229, v229, v232, s[2:3]
	v_mul_f32_e32 v230, 0x37800000, v229
	v_cndmask_b32_e64 v229, v229, v230, s[0:1]
	v_cmp_class_f32_e64 s[0:1], v228, v176
	s_waitcnt vmcnt(58)
	v_lshlrev_b32_e32 v154, 16, v154
	v_lshlrev_b32_e32 v157, 16, v157
	v_cndmask_b32_e64 v228, v229, v228, s[0:1]
	s_waitcnt lgkmcnt(0)
	s_nop 1
	v_add_f32_dpp v230, v220, v220 row_half_mirror row_mask:0xf bank_mask:0xf
	v_div_fmas_f32 v220, v226, v233, v231
	v_div_fixup_f32 v220, v220, v227, 1.0
	v_div_scale_f32 v229, s[0:1], v228, v228, 1.0
	s_waitcnt lgkmcnt(0)
	s_nop 1
	v_add_f32_dpp v227, v230, v230 row_mirror row_mask:0xf bank_mask:0xf
	v_rcp_f32_e32 v232, v229
	v_mul_f32_e32 v154, 0xbfb8aa3b, v154
	s_waitcnt vmcnt(57)
	v_lshlrev_b32_e32 v152, 16, v152
	s_waitcnt lgkmcnt(0)
	v_mov_b32_e32 v230, v227
	s_nop 1
	v_permlane16_swap_b32_e32 v227, v230
	v_add_f32_e32 v227, v227, v230
	v_fmamk_f32 v227, v227, 0x3c000000, v177
	v_mul_f32_e32 v230, 0x4f800000, v227
	v_cmp_gt_f32_e64 s[0:1], s49, v227
	v_fma_f32 v226, -v229, v232, 1.0
	v_fmac_f32_e32 v232, v226, v232
	v_cndmask_b32_e64 v227, v227, v230, s[0:1]
	v_div_scale_f32 v226, vcc, 1.0, v228, 1.0
	v_sqrt_f32_e32 v230, v227
	v_mul_f32_e32 v231, v226, v232
	v_fma_f32 v233, -v229, v231, v226
	v_fmac_f32_e32 v231, v233, v232
	v_fma_f32 v226, -v229, v231, v226
	v_add_u32_e32 v229, -1, v230
	s_waitcnt lgkmcnt(0)
	s_nop 1
	v_add_f32_dpp v217, v217, v217 quad_perm:[1,0,3,2] row_mask:0xf bank_mask:0xf
	v_fma_f32 v233, -v229, v230, v227
	v_cmp_ge_f32_e64 s[2:3], 0, v233
	v_add_u32_e32 v233, 1, v230
	v_mul_f32_e32 v157, 0xbfb8aa3b, v157
	v_cndmask_b32_e64 v229, v230, v229, s[2:3]
	v_fma_f32 v230, -v233, v230, v227
	v_cmp_lt_f32_e64 s[2:3], 0, v230
	s_waitcnt lgkmcnt(0)
	s_nop 1
	v_add_f32_dpp v217, v217, v217 quad_perm:[2,3,0,1] row_mask:0xf bank_mask:0xf
	v_exp_f32_e32 v154, v154
	v_cndmask_b32_e64 v229, v229, v233, s[2:3]
	v_mul_f32_e32 v230, 0x37800000, v229
	v_cndmask_b32_e64 v229, v229, v230, s[0:1]
	v_cmp_class_f32_e64 s[0:1], v227, v176
	v_mul_f32_e32 v152, 0xbfb8aa3b, v152
	s_waitcnt vmcnt(56)
	v_lshlrev_b32_e32 v149, 16, v149
	v_cndmask_b32_e64 v227, v229, v227, s[0:1]
	s_waitcnt lgkmcnt(0)
	s_nop 1
	v_add_f32_dpp v230, v217, v217 row_half_mirror row_mask:0xf bank_mask:0xf
	v_div_fmas_f32 v217, v226, v232, v231
	v_div_fixup_f32 v217, v217, v228, 1.0
	v_div_scale_f32 v229, s[0:1], v227, v227, 1.0
	s_waitcnt lgkmcnt(0)
	s_nop 1
	v_add_f32_dpp v228, v230, v230 row_mirror row_mask:0xf bank_mask:0xf
	v_rcp_f32_e32 v233, v229
	v_add_f32_e32 v154, 1.0, v154
	v_mul_f32_e32 v149, 0xbfb8aa3b, v149
	s_waitcnt lgkmcnt(0)
	v_mov_b32_e32 v230, v228
	s_nop 1
	v_permlane16_swap_b32_e32 v228, v230
	v_add_f32_e32 v228, v228, v230
	v_fmamk_f32 v228, v228, 0x3c000000, v177
	v_mul_f32_e32 v230, 0x4f800000, v228
	v_cmp_gt_f32_e64 s[0:1], s49, v228
	v_fma_f32 v226, -v229, v233, 1.0
	v_fmac_f32_e32 v233, v226, v233
	v_cndmask_b32_e64 v228, v228, v230, s[0:1]
	v_div_scale_f32 v226, vcc, 1.0, v227, 1.0
	v_sqrt_f32_e32 v230, v228
	v_mul_f32_e32 v231, v226, v233
	v_fma_f32 v232, -v229, v231, v226
	v_fmac_f32_e32 v231, v232, v233
	v_fma_f32 v226, -v229, v231, v226
	v_add_u32_e32 v229, -1, v230
	s_waitcnt lgkmcnt(0)
	s_nop 1
	v_add_f32_dpp v214, v214, v214 quad_perm:[1,0,3,2] row_mask:0xf bank_mask:0xf
	v_fma_f32 v232, -v229, v230, v228
	v_cmp_ge_f32_e64 s[2:3], 0, v232
	v_add_u32_e32 v232, 1, v230
	v_lshlrev_b32_e32 v165, 16, v165
	v_cndmask_b32_e64 v229, v230, v229, s[2:3]
	v_fma_f32 v230, -v232, v230, v228
	v_cmp_lt_f32_e64 s[2:3], 0, v230
	s_waitcnt lgkmcnt(0)
	s_nop 1
	v_add_f32_dpp v214, v214, v214 quad_perm:[2,3,0,1] row_mask:0xf bank_mask:0xf
	v_mul_f32_e32 v165, 0xbfb8aa3b, v165
	v_cndmask_b32_e64 v229, v229, v232, s[2:3]
	v_mul_f32_e32 v230, 0x37800000, v229
	v_cndmask_b32_e64 v229, v229, v230, s[0:1]
	v_cmp_class_f32_e64 s[0:1], v228, v176
	s_waitcnt vmcnt(55)
	v_lshlrev_b32_e32 v151, 16, v151
	s_waitcnt vmcnt(54)
	v_lshlrev_b32_e32 v148, 16, v148
	v_cndmask_b32_e64 v228, v229, v228, s[0:1]
	s_waitcnt lgkmcnt(0)
	s_nop 1
	v_add_f32_dpp v230, v214, v214 row_half_mirror row_mask:0xf bank_mask:0xf
	v_div_fmas_f32 v214, v226, v233, v231
	v_div_fixup_f32 v214, v214, v227, 1.0
	v_div_scale_f32 v229, s[0:1], v228, v228, 1.0
	s_waitcnt lgkmcnt(0)
	s_nop 1
	v_add_f32_dpp v227, v230, v230 row_mirror row_mask:0xf bank_mask:0xf
	v_rcp_f32_e32 v232, v229
	v_exp_f32_e32 v165, v165
	s_waitcnt lgkmcnt(0)
; __device__ __forceinline__ void attn_unit_pp(int b, int h, int qb, int par, const bf16_t* __restrict__ QBp, const bf16_t* __restrict__ KBp, const bf16_t* __restrict__ VBp, ...
;     ...
;     for (int r = 0; r < 16; ++r) { float s = ss[r];
; #pragma unroll
;       for (int x = 1; x < 32; x <<= 1) s += __builtin_bit_cast(float, __builtin_amdgcn_ds_bpermute((lane ^ x) << 2, __builtin_bit_cast(int, s)));
;       ss[r] = 1.0f / sqrtf(s * (1.0f / 128.0f) + 1e-5f); }
;     float sg[4];
; #pragma unroll
;     for (int d0 = 0; d0 < 4; ++d0) sg[d0] = sub_g[d0 * 32 + r32] * 0.8f;
	v_mov_b32_e32 v230, v227
	s_nop 1
	v_permlane16_swap_b32_e32 v227, v230
	v_add_f32_e32 v227, v227, v230
	v_fmamk_f32 v227, v227, 0x3c000000, v177
	v_mul_f32_e32 v230, 0x4f800000, v227
	v_cmp_gt_f32_e64 s[0:1], s49, v227
	v_fma_f32 v226, -v229, v232, 1.0
	v_fmac_f32_e32 v232, v226, v232
	v_cndmask_b32_e64 v227, v227, v230, s[0:1]
	v_div_scale_f32 v226, vcc, 1.0, v228, 1.0
	v_sqrt_f32_e32 v230, v227
	v_mul_f32_e32 v231, v226, v232
	v_fma_f32 v233, -v229, v231, v226
	v_fmac_f32_e32 v231, v233, v232
	v_fma_f32 v226, -v229, v231, v226
	v_add_u32_e32 v229, -1, v230
	s_waitcnt lgkmcnt(0)
	s_nop 1
	v_add_f32_dpp v213, v213, v213 quad_perm:[1,0,3,2] row_mask:0xf bank_mask:0xf
	v_fma_f32 v233, -v229, v230, v227
	v_cmp_ge_f32_e64 s[2:3], 0, v233
	v_add_u32_e32 v233, 1, v230
	s_waitcnt lgkmcnt(0)
	s_nop 1
	v_add_f32_dpp v183, v211, v211 quad_perm:[1,0,3,2] row_mask:0xf bank_mask:0xf
	v_cndmask_b32_e64 v229, v230, v229, s[2:3]
	v_fma_f32 v230, -v233, v230, v227
	v_cmp_lt_f32_e64 s[2:3], 0, v230
	s_waitcnt lgkmcnt(0)
	s_nop 1
	v_add_f32_dpp v213, v213, v213 quad_perm:[2,3,0,1] row_mask:0xf bank_mask:0xf
	v_cndmask_b32_e64 v229, v229, v233, s[2:3]
	v_mul_f32_e32 v230, 0x37800000, v229
	v_cndmask_b32_e64 v229, v229, v230, s[0:1]
	v_cmp_class_f32_e64 s[0:1], v227, v176
	s_waitcnt lgkmcnt(0)
	s_nop 1
	v_add_f32_dpp v182, v183, v183 quad_perm:[2,3,0,1] row_mask:0xf bank_mask:0xf
	v_cndmask_b32_e64 v227, v229, v227, s[0:1]
	s_waitcnt lgkmcnt(0)
	s_nop 1
	v_add_f32_dpp v230, v213, v213 row_half_mirror row_mask:0xf bank_mask:0xf
	v_div_fmas_f32 v213, v226, v232, v231
	v_lshlrev_b32_e32 v232, 2, v179
	v_div_fixup_f32 v213, v213, v228, 1.0
	v_div_scale_f32 v229, s[0:1], v227, v227, 1.0
	s_waitcnt lgkmcnt(0)
	s_nop 1
	v_add_f32_dpp v228, v230, v230 row_mirror row_mask:0xf bank_mask:0xf
	global_load_dword v234, v232, s[54:55]
	global_load_dword v235, v232, s[54:55] offset:128
	global_load_dword v236, v232, s[54:55] offset:256
	v_rcp_f32_e32 v233, v229
	global_load_dword v237, v232, s[54:55] offset:384
	s_nop 1
	v_add_f32_dpp v181, v182, v182 row_half_mirror row_mask:0xf bank_mask:0xf
	s_waitcnt lgkmcnt(0)
	v_mov_b32_e32 v230, v228
	s_nop 1
	v_permlane16_swap_b32_e32 v228, v230
	v_add_f32_e32 v228, v228, v230
	v_fmamk_f32 v228, v228, 0x3c000000, v177
	v_mul_f32_e32 v230, 0x4f800000, v228
	v_cmp_gt_f32_e64 s[0:1], s49, v228
	v_fma_f32 v226, -v229, v233, 1.0
	v_fmac_f32_e32 v233, v226, v233
	v_cndmask_b32_e64 v228, v228, v230, s[0:1]
	v_div_scale_f32 v226, vcc, 1.0, v227, 1.0
	v_sqrt_f32_e32 v230, v228
	v_mul_f32_e32 v231, v226, v233
	v_fma_f32 v232, -v229, v231, v226
	v_fmac_f32_e32 v231, v232, v233
	v_fma_f32 v226, -v229, v231, v226
	v_add_u32_e32 v229, -1, v230
	v_fma_f32 v232, -v229, v230, v228
	v_cmp_ge_f32_e64 s[2:3], 0, v232
	v_add_u32_e32 v232, 1, v230
	s_waitcnt lgkmcnt(0)
	s_nop 1
	v_add_f32_dpp v180, v181, v181 row_mirror row_mask:0xf bank_mask:0xf
	v_cndmask_b32_e64 v229, v230, v229, s[2:3]
	v_fma_f32 v230, -v232, v230, v228
	v_cmp_lt_f32_e64 s[2:3], 0, v230
	v_div_fmas_f32 v182, v226, v233, v231
	v_cndmask_b32_e64 v211, v229, v232, s[2:3]
	v_mul_f32_e32 v229, 0x37800000, v211
	v_cndmask_b32_e64 v211, v211, v229, s[0:1]
	v_cmp_class_f32_e64 s[0:1], v228, v176
	s_waitcnt lgkmcnt(0)
	v_mov_b32_e32 v169, v180
	s_nop 1
	v_permlane16_swap_b32_e32 v180, v169
	v_add_f32_e32 v169, v180, v169
	v_fmamk_f32 v169, v169, 0x3c000000, v177
	v_cndmask_b32_e64 v183, v211, v228, s[0:1]
	v_div_scale_f32 v211, s[0:1], v183, v183, 1.0
	v_rcp_f32_e32 v228, v211
	v_mul_f32_e32 v180, 0x4f800000, v169
	v_cmp_gt_f32_e64 s[0:1], s49, v169
	v_div_fixup_f32 v232, v182, v227, 1.0
	v_fma_f32 v182, -v211, v228, 1.0
	v_cndmask_b32_e64 v169, v169, v180, s[0:1]
	v_fmac_f32_e32 v228, v182, v228
	v_div_scale_f32 v181, vcc, 1.0, v183, 1.0
	v_sqrt_f32_e32 v180, v169
	v_mul_f32_e32 v182, v181, v228
	v_fma_f32 v226, -v211, v182, v181
	v_fmac_f32_e32 v182, v226, v228
	v_fma_f32 v181, -v211, v182, v181
	v_add_u32_e32 v211, -1, v180
	v_fma_f32 v226, -v211, v180, v169
	v_cmp_ge_f32_e64 s[2:3], 0, v226
	v_add_u32_e32 v226, 1, v180
	v_div_fmas_f32 v181, v181, v228, v182
	v_cndmask_b32_e64 v211, v180, v211, s[2:3]
	v_fma_f32 v180, -v226, v180, v169
	v_cmp_lt_f32_e64 s[2:3], 0, v180
	v_div_fixup_f32 v230, v181, v183, 1.0
	v_mul_f32_e32 v151, 0xbfb8aa3b, v151
	v_cndmask_b32_e64 v180, v211, v226, s[2:3]
	v_mul_f32_e32 v211, 0x37800000, v180
	v_cndmask_b32_e64 v180, v180, v211, s[0:1]
	v_cmp_class_f32_e64 s[0:1], v169, v176
	v_mul_f32_e32 v148, 0xbfb8aa3b, v148
	s_waitcnt vmcnt(57)
	v_lshlrev_b32_e32 v147, 16, v147
	v_cndmask_b32_e64 v169, v180, v169, s[0:1]
	v_div_scale_f32 v180, s[0:1], v169, v169, 1.0
	v_rcp_f32_e32 v211, v180
	s_waitcnt vmcnt(55)
	v_lshlrev_b32_e32 v141, 16, v141
	v_exp_f32_e32 v148, v148
	v_mul_f32_e32 v147, 0xbfb8aa3b, v147
	v_fma_f32 v181, -v180, v211, 1.0
	v_fmac_f32_e32 v211, v181, v211
	v_div_scale_f32 v181, vcc, 1.0, v169, 1.0
	v_mul_f32_e32 v182, v181, v211
	v_fma_f32 v183, -v180, v182, v181
	v_fmac_f32_e32 v182, v183, v211
	v_fma_f32 v180, -v180, v182, v181
	v_div_fmas_f32 v180, v180, v211, v182
	v_div_fixup_f32 v226, v180, v169, 1.0
	v_exp_f32_e32 v180, v162
	s_waitcnt vmcnt(3)
; __device__ __forceinline__ float sigm_(float x) { return __builtin_amdgcn_rcpf(1.0f + __builtin_amdgcn_exp2f(-1.4426950408889634f * x)); }
; __device__ __forceinline__ void attn_unit_pp(int b, int h, int qb, int par, const bf16_t* __restrict__ QBp, const bf16_t* __restrict__ KBp, const bf16_t* __restrict__ VBp, ...
;     ...
;     for (int d0 = 0; d0 < 4; ++d0) sg[d0] = sub_g[d0 * 32 + r32] * 0.8f;
; #pragma unroll
;     for (int r = 0; r < 16; ++r)
; #pragma unroll
;       for (int d0 = 0; d0 < 4; ++d0) { const float ga = __uint_as_float(gate16[r * 4 + d0] << 16); o[d0][r] = o[d0][r] * ss[r] * sg[d0] * sigm_(ga); }
	v_mul_f32_e32 v231, 0x3f4ccccd, v234
	v_mul_f32_e32 v169, v198, v215
	v_mul_f32_e32 v198, v169, v231
	v_rcp_f32_e32 v169, v163
	v_add_f32_e32 v163, 1.0, v180
	v_exp_f32_e32 v180, v159
	v_exp_f32_e32 v181, v157
	v_exp_f32_e32 v182, v152
	v_exp_f32_e32 v183, v151
	v_add_f32_e32 v180, 1.0, v180
	v_rcp_f32_e32 v157, v180
	v_mul_f32_e32 v180, v194, v216
	v_mul_f32_e32 v194, v180, v231
	v_add_f32_e32 v180, 1.0, v181
	v_rcp_f32_e32 v181, v154
	v_add_f32_e32 v154, 1.0, v182
	v_exp_f32_e32 v182, v149
	v_mul_f32_e32 v141, 0xbfb8aa3b, v141
	v_add_f32_e32 v165, 1.0, v165
	v_lshlrev_b32_e32 v143, 16, v143
	v_add_f32_e32 v182, 1.0, v182
	v_rcp_f32_e32 v151, v182
	v_mul_f32_e32 v182, v190, v218
	v_exp_f32_e32 v190, v147
	v_mul_f32_e32 v147, v205, v218
	v_exp_f32_e32 v205, v141
	v_lshlrev_b32_e32 v139, 16, v139
	v_rcp_f32_e32 v211, v165
	v_mul_f32_e32 v165, v202, v215
	v_rcp_f32_e32 v202, v180
	v_mul_f32_e32 v180, v199, v216
	v_mul_f32_e32 v199, v182, v231
	v_add_f32_e32 v182, 1.0, v183
	v_add_f32_e32 v148, 1.0, v148
	v_mul_f32_e32 v143, 0xbfb8aa3b, v143
	v_mul_f32_e32 v186, v186, v219
	v_mul_f32_e32 v139, 0xbfb8aa3b, v139
	v_lshlrev_b32_e32 v138, 16, v138
	v_mul_f32_e32 v152, v207, v216
	v_rcp_f32_e32 v207, v182
	v_mul_f32_e32 v182, v195, v218
	v_rcp_f32_e32 v183, v148
	v_add_f32_e32 v148, 1.0, v190
	v_exp_f32_e32 v190, v143
	v_mul_f32_e32 v195, v186, v231
	v_add_f32_e32 v186, 1.0, v205
	v_exp_f32_e32 v139, v139
	v_mul_f32_e32 v138, 0xbfb8aa3b, v138
	v_rcp_f32_e32 v205, v186
	v_mul_f32_e32 v186, v191, v219
	v_exp_f32_e32 v191, v138
	v_lshlrev_b32_e32 v134, 16, v134
	v_add_f32_e32 v190, 1.0, v190
	v_add_f32_e32 v139, 1.0, v139
	v_mul_f32_e32 v134, 0xbfb8aa3b, v134
	v_lshlrev_b32_e32 v137, 16, v137
	v_lshlrev_b32_e32 v133, 16, v133
	v_rcp_f32_e32 v141, v190
	v_rcp_f32_e32 v190, v139
	v_add_f32_e32 v139, 1.0, v191
	v_exp_f32_e32 v191, v134
	v_mul_f32_e32 v137, 0xbfb8aa3b, v137
	v_mul_f32_e32 v133, 0xbfb8aa3b, v133
	v_lshlrev_b32_e32 v131, 16, v131
	v_mul_f32_e32 v138, v201, v219
	v_exp_f32_e32 v201, v137
	v_exp_f32_e32 v133, v133
	v_mul_f32_e32 v131, 0xbfb8aa3b, v131
	v_mul_f32_e32 v134, v206, v219
	v_exp_f32_e32 v206, v131
	v_add_f32_e32 v191, 1.0, v191
	v_mul_f32_e32 v171, v171, v221
	v_lshlrev_b32_e32 v124, 16, v124
	v_lshlrev_b32_e32 v122, 16, v122
	v_rcp_f32_e32 v137, v191
	v_mul_f32_e32 v191, v171, v231
	v_add_f32_e32 v171, 1.0, v201
	v_add_f32_e32 v133, 1.0, v133
	v_mul_f32_e32 v124, 0xbfb8aa3b, v124
	v_mul_f32_e32 v122, 0xbfb8aa3b, v122
	v_rcp_f32_e32 v201, v171
	v_mul_f32_e32 v171, v187, v221
	v_rcp_f32_e32 v187, v133
	v_add_f32_e32 v133, 1.0, v206
	v_lshlrev_b32_e32 v130, 16, v130
	v_exp_f32_e32 v206, v124
	v_mul_f32_e32 v124, v192, v222
	v_exp_f32_e32 v192, v122
	v_mul_f32_e32 v130, 0xbfb8aa3b, v130
	v_lshlrev_b32_e32 v129, 16, v129
	v_lshlrev_b32_e32 v126, 16, v126
	v_mul_f32_e32 v131, v197, v221
	v_exp_f32_e32 v197, v130
	v_mul_f32_e32 v129, 0xbfb8aa3b, v129
	v_mul_f32_e32 v126, 0xbfb8aa3b, v126
	v_lshlrev_b32_e32 v123, 16, v123
	v_lshlrev_b32_e32 v121, 16, v121
	v_mul_f32_e32 v130, v204, v221
	v_exp_f32_e32 v204, v129
	v_exp_f32_e32 v126, v126
	v_mul_f32_e32 v123, 0xbfb8aa3b, v123
	v_mul_f32_e32 v121, 0xbfb8aa3b, v121
	v_lshlrev_b32_e32 v120, 16, v120
	v_lshlrev_b32_e32 v117, 16, v117
	v_mul_f32_e32 v122, v203, v222
	v_add_f32_e32 v192, 1.0, v192
	v_exp_f32_e32 v203, v123
	v_exp_f32_e32 v121, v121
	v_mul_f32_e32 v120, 0xbfb8aa3b, v120
	v_mul_f32_e32 v117, 0xbfb8aa3b, v117
	v_rcp_f32_e32 v123, v192
	v_exp_f32_e32 v192, v120
	v_mul_f32_e32 v120, v188, v223
	v_exp_f32_e32 v188, v117
	v_add_f32_e32 v197, 1.0, v197
	v_mul_f32_e32 v161, v161, v222
	v_rcp_f32_e32 v129, v197
	v_mul_f32_e32 v197, v161, v231
	v_add_f32_e32 v161, 1.0, v204
	v_add_f32_e32 v126, 1.0, v126
	v_mul_f32_e32 v150, v150, v223
	v_lshlrev_b32_e32 v115, 16, v115
	v_lshlrev_b32_e32 v114, 16, v114
	v_rcp_f32_e32 v204, v161
	v_mul_f32_e32 v161, v172, v222
	v_rcp_f32_e32 v172, v126
	v_add_f32_e32 v126, 1.0, v206
	v_mul_f32_e32 v206, v150, v231
	v_add_f32_e32 v150, 1.0, v203
	v_add_f32_e32 v121, 1.0, v121
	v_mul_f32_e32 v115, 0xbfb8aa3b, v115
	v_mul_f32_e32 v114, 0xbfb8aa3b, v114
	v_lshlrev_b32_e32 v113, 16, v113
	v_lshlrev_b32_e32 v109, 16, v109
	v_rcp_f32_e32 v203, v150
	v_mul_f32_e32 v150, v167, v223
	v_rcp_f32_e32 v167, v121
	v_add_f32_e32 v121, 1.0, v192
	v_add_f32_e32 v188, 1.0, v188
	v_exp_f32_e32 v192, v115
	v_exp_f32_e32 v114, v114
	v_mul_f32_e32 v113, 0xbfb8aa3b, v113
	v_mul_f32_e32 v109, 0xbfb8aa3b, v109
	v_rcp_f32_e32 v115, v188
	v_exp_f32_e32 v188, v113
	v_mul_f32_e32 v113, v184, v225
	v_exp_f32_e32 v184, v109
	v_mul_f32_e32 v140, v140, v225
	v_lshlrev_b32_e32 v110, 16, v110
	v_lshlrev_b32_e32 v108, 16, v108
	v_mul_f32_e32 v117, v200, v223
	v_mul_f32_e32 v200, v140, v231
	v_add_f32_e32 v140, 1.0, v192
	v_add_f32_e32 v114, 1.0, v114
	v_mul_f32_e32 v110, 0xbfb8aa3b, v110
	v_mul_f32_e32 v108, 0xbfb8aa3b, v108
	v_lshlrev_b32_e32 v106, 16, v106
	v_mul_f32_e32 v143, v208, v218
	v_rcp_f32_e32 v208, v140
	v_mul_f32_e32 v140, v158, v225
	v_rcp_f32_e32 v158, v114
	v_add_f32_e32 v114, 1.0, v188
	v_add_f32_e32 v184, 1.0, v184
	v_exp_f32_e32 v188, v110
	v_exp_f32_e32 v108, v108
	v_mul_f32_e32 v106, 0xbfb8aa3b, v106
	v_rcp_f32_e32 v110, v184
	v_exp_f32_e32 v184, v106
	v_lshlrev_b32_e32 v105, 16, v105
	v_mul_f32_e32 v132, v132, v224
	v_mul_f32_e32 v105, 0xbfb8aa3b, v105
	v_lshlrev_b32_e32 v104, 16, v104
	v_mul_f32_e32 v109, v196, v225
	v_mul_f32_e32 v196, v132, v231
	v_add_f32_e32 v132, 1.0, v188
	v_add_f32_e32 v108, 1.0, v108
	v_mul_f32_e32 v106, v173, v224
	v_exp_f32_e32 v173, v105
	v_mul_f32_e32 v104, 0xbfb8aa3b, v104
	v_mul_f32_e32 v162, v209, v215
	v_rcp_f32_e32 v209, v132
; __device__ __forceinline__ float sigm_(float x) { return __builtin_amdgcn_rcpf(1.0f + __builtin_amdgcn_exp2f(-1.4426950408889634f * x)); }
; __device__ __forceinline__ void attn_unit_pp(int b, int h, int qb, int par, const bf16_t* __restrict__ QBp, const bf16_t* __restrict__ KBp, const bf16_t* __restrict__ VBp, ...
;     ...
;       for (int d0 = 0; d0 < 4; ++d0) { const float ga = __uint_as_float(gate16[r * 4 + d0] << 16); o[d0][r] = o[d0][r] * ss[r] * sg[d0] * sigm_(ga); }
;     __syncthreads();
; #pragma unroll
;     for (int d0 = 0; d0 < 4; ++d0)
; #pragma unroll
;       for (int r = 0; r < 16; ++r) { const int ro = (r & 3) + 8 * (r >> 2);
;         const float val = o[d0][r] + pgs[(d0 * 16 + r) * 64];
;         unsigned u = __float_as_uint(val); u = (u + 0x7fffu + ((u >> 16) & 1u)) >> 16;
;         MIX_ST(ro, d0 * 32, (unsigned short)u); }
	v_mul_f32_e32 v132, v155, v224
	v_rcp_f32_e32 v155, v108
	v_add_f32_e32 v108, 1.0, v184
	v_exp_f32_e32 v184, v104
	v_lshlrev_b32_e32 v102, 16, v102
	v_mul_f32_e32 v102, 0xbfb8aa3b, v102
	v_lshlrev_b32_e32 v65, 16, v65
	v_add_f32_e32 v173, 1.0, v173
	v_mul_f32_e32 v125, v125, v220
	v_exp_f32_e32 v102, v102
	v_mul_f32_e32 v65, 0xbfb8aa3b, v65
	v_rcp_f32_e32 v104, v173
	v_mul_f32_e32 v173, v125, v231
	v_add_f32_e32 v125, 1.0, v184
	v_exp_f32_e32 v184, v65
	v_lshlrev_b32_e32 v63, 16, v63
	v_mul_f32_e32 v63, 0xbfb8aa3b, v63
	v_lshlrev_b32_e32 v64, 16, v64
	v_add_f32_e32 v102, 1.0, v102
	v_mul_f32_e32 v65, v164, v220
	v_exp_f32_e32 v164, v63
	v_mul_f32_e32 v64, 0xbfb8aa3b, v64
	v_mul_f32_e32 v149, v210, v216
	v_rcp_f32_e32 v210, v125
	v_mul_f32_e32 v125, v145, v220
	v_rcp_f32_e32 v145, v102
	v_add_f32_e32 v102, 1.0, v184
	v_exp_f32_e32 v184, v64
	v_lshlrev_b32_e32 v62, 16, v62
	v_mul_f32_e32 v62, 0xbfb8aa3b, v62
	v_lshlrev_b32_e32 v60, 16, v60
	v_add_f32_e32 v164, 1.0, v164
	v_exp_f32_e32 v62, v62
	v_mul_f32_e32 v60, 0xbfb8aa3b, v60
	v_rcp_f32_e32 v64, v164
	v_add_f32_e32 v164, 1.0, v184
	v_exp_f32_e32 v184, v60
	v_lshlrev_b32_e32 v59, 16, v59
	v_mul_f32_e32 v59, 0xbfb8aa3b, v59
	v_lshlrev_b32_e32 v57, 16, v57
	v_add_f32_e32 v62, 1.0, v62
	v_mul_f32_e32 v60, v156, v217
	v_exp_f32_e32 v156, v59
	v_mul_f32_e32 v57, 0xbfb8aa3b, v57
	v_mul_f32_e32 v159, v212, v215
	v_rcp_f32_e32 v212, v62
	v_add_f32_e32 v62, 1.0, v184
	v_exp_f32_e32 v184, v57
	v_lshlrev_b32_e32 v52, 16, v52
	v_lshlrev_b32_e32 v55, 16, v55
	v_lshlrev_b32_e32 v53, 16, v53
	v_mul_f32_e32 v52, 0xbfb8aa3b, v52
	v_lshlrev_b32_e32 v50, 16, v50
	s_waitcnt vmcnt(2)
	v_mul_f32_e32 v229, 0x3f4ccccd, v235
	v_add_f32_e32 v156, 1.0, v156
	v_mul_f32_e32 v55, 0xbfb8aa3b, v55
	v_mul_f32_e32 v53, 0xbfb8aa3b, v53
	v_exp_f32_e32 v52, v52
	v_mul_f32_e32 v118, v118, v213
	v_mul_f32_e32 v50, 0xbfb8aa3b, v50
	v_rcp_f32_e32 v57, v156
	v_mul_f32_e32 v107, v107, v214
	v_add_f32_e32 v156, 1.0, v184
	v_mul_f32_e32 v127, v127, v214
	v_exp_f32_e32 v184, v55
	v_mul_f32_e32 v55, v146, v214
	v_exp_f32_e32 v146, v53
	v_mul_f32_e32 v53, v170, v214
	v_mul_f32_e32 v214, v118, v229
	v_exp_f32_e32 v118, v50
	v_lshlrev_b32_e32 v49, 16, v49
	v_add_f32_e32 v52, 1.0, v52
	v_mul_f32_e32 v49, 0xbfb8aa3b, v49
	v_lshlrev_b32_e32 v48, 16, v48
	v_rcp_f32_e32 v216, v52
	v_add_f32_e32 v52, 1.0, v118
	v_exp_f32_e32 v118, v49
	v_mul_f32_e32 v48, 0xbfb8aa3b, v48
	v_mul_f32_e32 v50, v136, v213
	v_exp_f32_e32 v136, v48
	v_lshlrev_b32_e32 v47, 16, v47
	v_add_f32_e32 v118, 1.0, v118
	v_mul_f32_e32 v47, 0xbfb8aa3b, v47
	v_lshlrev_b32_e32 v45, 16, v45
	v_rcp_f32_e32 v48, v118
	v_add_f32_e32 v118, 1.0, v136
	v_exp_f32_e32 v47, v47
	v_mul_f32_e32 v45, 0xbfb8aa3b, v45
	v_rcp_f32_e32 v136, v118
	v_exp_f32_e32 v118, v45
	v_lshlrev_b32_e32 v43, 16, v43
	v_add_f32_e32 v47, 1.0, v47
	v_mul_f32_e32 v43, 0xbfb8aa3b, v43
	v_lshlrev_b32_e32 v44, 16, v44
	v_mul_f32_e32 v101, v101, v213
	v_mul_f32_e32 v49, v160, v213
	v_rcp_f32_e32 v213, v47
	v_add_f32_e32 v47, 1.0, v118
	v_exp_f32_e32 v118, v43
	v_mul_f32_e32 v44, 0xbfb8aa3b, v44
	v_mul_f32_e32 v45, v128, v232
	v_exp_f32_e32 v128, v44
	v_add_f32_e32 v118, 1.0, v118
	v_lshlrev_b32_e32 v41, 16, v41
	v_rcp_f32_e32 v44, v118
	v_add_f32_e32 v118, 1.0, v128
	v_mul_f32_e32 v41, 0xbfb8aa3b, v41
	v_lshlrev_b32_e32 v40, 16, v40
	v_rcp_f32_e32 v128, v118
	v_exp_f32_e32 v118, v41
	v_mul_f32_e32 v40, 0xbfb8aa3b, v40
	v_mul_f32_e32 v41, v119, v230
	v_exp_f32_e32 v119, v40
	v_lshlrev_b32_e32 v39, 16, v39
	v_add_f32_e32 v118, 1.0, v118
	v_mul_f32_e32 v39, 0xbfb8aa3b, v39
	v_mul_f32_e32 v43, v153, v232
	v_rcp_f32_e32 v153, v118
	v_add_f32_e32 v118, 1.0, v119
	v_exp_f32_e32 v119, v39
	v_lshlrev_b32_e32 v37, 16, v37
	v_rcp_f32_e32 v39, v118
	v_mul_f32_e32 v37, 0xbfb8aa3b, v37
	v_add_f32_e32 v118, 1.0, v119
	v_lshlrev_b32_e32 v36, 16, v36
	s_waitcnt vmcnt(1)
	v_mul_f32_e32 v228, 0x3f4ccccd, v236
	v_lshlrev_b32_e32 v56, 16, v56
	v_mul_f32_e32 v40, v142, v230
	v_rcp_f32_e32 v142, v118
	v_exp_f32_e32 v37, v37
	v_mul_f32_e32 v112, v112, v226
	v_mul_f32_e32 v36, 0xbfb8aa3b, v36
	s_barrier
	ds_read2st64_b32 v[118:119], v68 offset1:1
	v_mul_f32_e32 v116, v116, v217
	v_mul_f32_e32 v135, v135, v217
	v_mul_f32_e32 v59, v185, v217
	v_mul_f32_e32 v56, 0xbfb8aa3b, v56
	v_mul_f32_e32 v217, v228, v112
	v_exp_f32_e32 v112, v36
	v_exp_f32_e32 v56, v56
	v_add_f32_e32 v37, 1.0, v37
	v_rcp_f32_e32 v218, v37
	v_add_f32_e32 v37, 1.0, v112
	s_waitcnt lgkmcnt(0)
	v_fma_f32 v112, v211, v198, v118
	v_add_f32_e32 v56, 1.0, v56
	v_bfe_u32 v118, v112, 16, 1
	v_mul_f32_e32 v105, v193, v224
	v_mul_f32_e32 v63, v189, v220
	v_rcp_f32_e32 v215, v56
	v_add_f32_e32 v56, 1.0, v184
	ds_read2st64_b32 v[184:185], v68 offset0:2 offset1:3
	ds_read2st64_b32 v[188:189], v68 offset0:4 offset1:5
	ds_read2st64_b32 v[192:193], v68 offset0:6 offset1:7
	v_add3_u32 v112, v112, v118, s66
	v_fmac_f32_e32 v119, v202, v194
	global_store_short_d16_hi v35, v112, s[24:25]
	v_bfe_u32 v112, v119, 16, 1
	v_add3_u32 v112, v119, v112, s66
	v_add_u32_e32 v118, 0x800, v35
	global_store_short_d16_hi v118, v112, s[24:25]
	s_waitcnt lgkmcnt(2)
	v_fma_f32 v112, v207, v199, v184
	v_bfe_u32 v118, v112, 16, 1
	v_add3_u32 v112, v112, v118, s66
	v_add_u32_e32 v118, 0x1000, v35
	v_fmac_f32_e32 v185, v205, v195
	global_store_short_d16_hi v118, v112, s[24:25]
	v_bfe_u32 v112, v185, 16, 1
	v_add3_u32 v112, v185, v112, s66
	v_add_u32_e32 v118, 0x1800, v35
	global_store_short_d16_hi v118, v112, s[24:25]
	s_waitcnt lgkmcnt(1)
; __device__ __forceinline__ void attn_unit_pp(int b, int h, int qb, int par, const bf16_t* __restrict__ QBp, const bf16_t* __restrict__ KBp, const bf16_t* __restrict__ VBp, ...
;     ...
; #pragma unroll
;     for (int d0 = 0; d0 < 4; ++d0)
; #pragma unroll
;       for (int r = 0; r < 16; ++r) { const int ro = (r & 3) + 8 * (r >> 2);
;         const float val = o[d0][r] + pgs[(d0 * 16 + r) * 64];
;         unsigned u = __float_as_uint(val); u = (u + 0x7fffu + ((u >> 16) & 1u)) >> 16;
;         MIX_ST(ro, d0 * 32, (unsigned short)u); }
	v_fma_f32 v112, v201, v191, v188
	v_bfe_u32 v118, v112, 16, 1
	v_add3_u32 v112, v112, v118, s66
	v_add_u32_e32 v118, 0x4000, v35
	v_fmac_f32_e32 v189, v204, v197
	global_store_short_d16_hi v118, v112, s[24:25]
	v_bfe_u32 v112, v189, 16, 1
	v_add3_u32 v112, v189, v112, s66
	v_add_u32_e32 v118, 0x4800, v35
	global_store_short_d16_hi v118, v112, s[24:25]
	s_waitcnt lgkmcnt(0)
	v_fma_f32 v112, v203, v206, v192
	v_bfe_u32 v118, v112, 16, 1
	v_add3_u32 v112, v112, v118, s66
	v_add_u32_e32 v118, 0x5000, v35
	global_store_short_d16_hi v118, v112, s[24:25]
	ds_read2st64_b32 v[118:119], v68 offset0:8 offset1:9
	v_lshlrev_b32_e32 v54, 16, v54
	v_fmac_f32_e32 v193, v208, v200
	v_mul_f32_e32 v54, 0xbfb8aa3b, v54
	v_bfe_u32 v112, v193, 16, 1
	v_exp_f32_e32 v170, v54
	v_mul_f32_e32 v36, v144, v226
	v_add3_u32 v112, v193, v112, s66
	v_add_u32_e32 v144, 0x5800, v35
	global_store_short_d16_hi v144, v112, s[24:25]
	s_waitcnt lgkmcnt(0)
	v_fma_f32 v112, v209, v196, v118
	v_rcp_f32_e32 v164, v164
	v_bfe_u32 v118, v112, 16, 1
	v_rcp_f32_e32 v156, v156
	v_add_f32_e32 v146, 1.0, v146
	ds_read2st64_b32 v[184:185], v68 offset0:10 offset1:11
	ds_read2st64_b32 v[188:189], v68 offset0:12 offset1:13
	ds_read2st64_b32 v[192:193], v68 offset0:14 offset1:15
	v_add3_u32 v112, v112, v118, s66
	v_add_u32_e32 v118, 0x8000, v35
	v_fmac_f32_e32 v119, v210, v173
	v_rcp_f32_e32 v54, v146
	v_add_f32_e32 v146, 1.0, v170
	global_store_short_d16_hi v118, v112, s[24:25]
	v_bfe_u32 v112, v119, 16, 1
	v_mul_f32_e32 v116, v116, v231
	v_rcp_f32_e32 v146, v146
	v_add3_u32 v112, v119, v112, s66
	v_add_u32_e32 v118, 0x8800, v35
	v_mul_f32_e32 v107, v107, v231
	global_store_short_d16_hi v118, v112, s[24:25]
	s_waitcnt lgkmcnt(2)
	v_fma_f32 v112, v164, v116, v184
	v_bfe_u32 v116, v112, 16, 1
	v_fmac_f32_e32 v185, v156, v107
	v_mul_f32_e32 v101, v101, v231
	v_mul_f32_e32 v58, v58, v232
	v_add3_u32 v112, v112, v116, s66
	v_add_u32_e32 v116, 0x9000, v35
	v_bfe_u32 v107, v185, 16, 1
	v_mul_f32_e32 v58, v58, v231
	global_store_short_d16_hi v116, v112, s[24:25]
	v_add3_u32 v107, v185, v107, s66
	v_add_u32_e32 v112, 0x9800, v35
	s_waitcnt lgkmcnt(1)
	v_fma_f32 v101, v146, v101, v188
	v_mul_f32_e32 v51, v51, v230
	global_store_short_d16_hi v112, v107, s[24:25]
	v_bfe_u32 v107, v101, 16, 1
	v_fmac_f32_e32 v189, v136, v58
	v_mul_f32_e32 v51, v51, v231
	v_mul_f32_e32 v46, v46, v226
	v_add3_u32 v101, v101, v107, s66
	v_add_u32_e32 v107, 0xc000, v35
	v_bfe_u32 v58, v189, 16, 1
	ds_read2st64_b32 v[118:119], v68 offset0:16 offset1:17
	v_mul_f32_e32 v46, v231, v46
	global_store_short_d16_hi v107, v101, s[24:25]
	v_add3_u32 v58, v189, v58, s66
	v_add_u32_e32 v101, 0xc800, v35
	s_waitcnt lgkmcnt(1)
	v_fma_f32 v51, v128, v51, v192
	global_store_short_d16_hi v101, v58, s[24:25]
	v_bfe_u32 v58, v51, 16, 1
	v_fmac_f32_e32 v193, v142, v46
	v_add3_u32 v51, v51, v58, s66
	v_add_u32_e32 v58, 0xd000, v35
	v_bfe_u32 v46, v193, 16, 1
	v_mul_f32_e32 v165, v165, v229
	global_store_short_d16_hi v58, v51, s[24:25]
	v_add3_u32 v46, v193, v46, s66
	v_add_u32_e32 v51, 0xd800, v35
	global_store_short_d16_hi v51, v46, s[24:25]
	s_waitcnt lgkmcnt(0)
	v_fma_f32 v51, v169, v165, v118
	v_mul_f32_e32 v180, v180, v229
	v_bfe_u32 v58, v51, 16, 1
	v_add_u32_e32 v46, 64, v35
	ds_read2st64_b32 v[184:185], v68 offset0:18 offset1:19
	ds_read2st64_b32 v[188:189], v68 offset0:20 offset1:21
	ds_read2st64_b32 v[192:193], v68 offset0:22 offset1:23
	v_add3_u32 v51, v51, v58, s66
	v_fmac_f32_e32 v119, v181, v180
	global_store_short_d16_hi v46, v51, s[24:25]
	v_bfe_u32 v46, v119, 16, 1
	v_mul_f32_e32 v182, v182, v229
	v_add3_u32 v46, v119, v46, s66
	v_add_u32_e32 v51, 0x840, v35
	global_store_short_d16_hi v51, v46, s[24:25]
	s_waitcnt lgkmcnt(2)
	v_fma_f32 v46, v183, v182, v184
	v_mul_f32_e32 v186, v186, v229
	v_bfe_u32 v51, v46, 16, 1
	v_add3_u32 v46, v46, v51, s66
	v_add_u32_e32 v51, 0x1040, v35
	v_fmac_f32_e32 v185, v190, v186
	global_store_short_d16_hi v51, v46, s[24:25]
	v_bfe_u32 v46, v185, 16, 1
	v_mul_f32_e32 v171, v171, v229
	v_add3_u32 v46, v185, v46, s66
	v_add_u32_e32 v51, 0x1840, v35
	global_store_short_d16_hi v51, v46, s[24:25]
	s_waitcnt lgkmcnt(1)
	v_fma_f32 v46, v187, v171, v188
	v_mul_f32_e32 v161, v161, v229
	v_bfe_u32 v51, v46, 16, 1
	v_add3_u32 v46, v46, v51, s66
	v_add_u32_e32 v51, 0x4040, v35
	v_fmac_f32_e32 v189, v172, v161
	global_store_short_d16_hi v51, v46, s[24:25]
	v_bfe_u32 v46, v189, 16, 1
	v_mul_f32_e32 v150, v150, v229
	v_add3_u32 v46, v189, v46, s66
	v_add_u32_e32 v51, 0x4840, v35
	global_store_short_d16_hi v51, v46, s[24:25]
	s_waitcnt lgkmcnt(0)
	v_fma_f32 v46, v167, v150, v192
	ds_read2st64_b32 v[118:119], v68 offset0:24 offset1:25
	v_mul_f32_e32 v140, v140, v229
	v_bfe_u32 v51, v46, 16, 1
	v_add3_u32 v46, v46, v51, s66
	v_add_u32_e32 v51, 0x5040, v35
	v_fmac_f32_e32 v193, v158, v140
	global_store_short_d16_hi v51, v46, s[24:25]
	v_bfe_u32 v46, v193, 16, 1
	v_mul_f32_e32 v132, v132, v229
	v_add3_u32 v46, v193, v46, s66
	v_add_u32_e32 v51, 0x5840, v35
	global_store_short_d16_hi v51, v46, s[24:25]
	s_waitcnt lgkmcnt(0)
	v_fma_f32 v46, v155, v132, v118
	v_mul_f32_e32 v125, v125, v229
	v_bfe_u32 v51, v46, 16, 1
	ds_read2st64_b32 v[160:161], v68 offset0:26 offset1:27
	ds_read2st64_b32 v[164:165], v68 offset0:28 offset1:29
	ds_read2st64_b32 v[170:171], v68 offset0:30 offset1:31
	v_add3_u32 v46, v46, v51, s66
	v_add_u32_e32 v51, 0x8040, v35
	v_fmac_f32_e32 v119, v145, v125
	v_lshlrev_b32_e32 v42, 16, v42
	global_store_short_d16_hi v51, v46, s[24:25]
	v_bfe_u32 v46, v119, 16, 1
	v_mul_f32_e32 v135, v135, v229
	v_mul_f32_e32 v42, 0xbfb8aa3b, v42
	v_lshlrev_b32_e32 v38, 16, v38
	v_add3_u32 v46, v119, v46, s66
	v_add_u32_e32 v51, 0x8840, v35
	v_exp_f32_e32 v42, v42
	v_mul_f32_e32 v38, 0xbfb8aa3b, v38
	global_store_short_d16_hi v51, v46, s[24:25]
	s_waitcnt lgkmcnt(2)
; __device__ __forceinline__ void attn_unit_pp(int b, int h, int qb, int par, const bf16_t* __restrict__ QBp, const bf16_t* __restrict__ KBp, const bf16_t* __restrict__ VBp, ...
;     ...
; #pragma unroll
;     for (int d0 = 0; d0 < 4; ++d0)
; #pragma unroll
;       for (int r = 0; r < 16; ++r) { const int ro = (r & 3) + 8 * (r >> 2);
;         const float val = o[d0][r] + pgs[(d0 * 16 + r) * 64];
;         unsigned u = __float_as_uint(val); u = (u + 0x7fffu + ((u >> 16) & 1u)) >> 16;
;         MIX_ST(ro, d0 * 32, (unsigned short)u); }
	v_fma_f32 v46, v212, v135, v160
	v_mul_f32_e32 v127, v127, v229
	v_exp_f32_e32 v38, v38
	v_bfe_u32 v51, v46, 16, 1
	v_add3_u32 v46, v46, v51, s66
	v_add_u32_e32 v51, 0x9040, v35
	v_fmac_f32_e32 v161, v215, v127
	global_store_short_d16_hi v51, v46, s[24:25]
	v_bfe_u32 v46, v161, 16, 1
	v_add_f32_e32 v42, 1.0, v42
	v_add3_u32 v46, v161, v46, s66
	v_add_u32_e32 v51, 0x9840, v35
	v_mul_f32_e32 v111, v111, v232
	v_rcp_f32_e32 v42, v42
	v_add_f32_e32 v38, 1.0, v38
	global_store_short_d16_hi v51, v46, s[24:25]
	s_waitcnt lgkmcnt(1)
	v_fma_f32 v46, v216, v214, v164
	v_mul_f32_e32 v111, v111, v229
	v_rcp_f32_e32 v38, v38
	v_bfe_u32 v51, v46, 16, 1
	v_mul_f32_e32 v103, v103, v230
	v_add3_u32 v46, v46, v51, s66
	v_add_u32_e32 v51, 0xc040, v35
	v_fmac_f32_e32 v165, v213, v111
	v_mul_f32_e32 v103, v103, v229
	v_mul_f32_e32 v61, v61, v226
	global_store_short_d16_hi v51, v46, s[24:25]
	v_bfe_u32 v46, v165, 16, 1
	ds_read2st64_b32 v[118:119], v68 offset0:32 offset1:33
	v_rcp_f32_e32 v163, v163
	v_mul_f32_e32 v61, v229, v61
	v_add3_u32 v46, v165, v46, s66
	v_add_u32_e32 v51, 0xc840, v35
	s_waitcnt lgkmcnt(1)
	v_fma_f32 v42, v42, v103, v170
	global_store_short_d16_hi v51, v46, s[24:25]
	v_bfe_u32 v46, v42, 16, 1
	v_fmac_f32_e32 v171, v38, v61
	v_rcp_f32_e32 v154, v154
	v_add3_u32 v42, v42, v46, s66
	v_add_u32_e32 v46, 0xd040, v35
	v_bfe_u32 v38, v171, 16, 1
	v_mul_f32_e32 v162, v162, v228
	global_store_short_d16_hi v46, v42, s[24:25]
	v_add3_u32 v38, v171, v38, s66
	v_add_u32_e32 v42, 0xd840, v35
	global_store_short_d16_hi v42, v38, s[24:25]
	s_waitcnt lgkmcnt(0)
	v_fma_f32 v42, v163, v162, v118
	v_mul_f32_e32 v152, v152, v228
	v_rcp_f32_e32 v148, v148
	v_bfe_u32 v46, v42, 16, 1
	v_add_u32_e32 v38, 0x80, v35
	ds_read2st64_b32 v[144:145], v68 offset0:34 offset1:35
	ds_read2st64_b32 v[160:161], v68 offset0:36 offset1:37
	ds_read2st64_b32 v[164:165], v68 offset0:38 offset1:39
	v_add3_u32 v42, v42, v46, s66
	v_fmac_f32_e32 v119, v154, v152
	v_rcp_f32_e32 v139, v139
	global_store_short_d16_hi v38, v42, s[24:25]
	v_bfe_u32 v38, v119, 16, 1
	v_mul_f32_e32 v147, v147, v228
	v_add3_u32 v38, v119, v38, s66
	v_add_u32_e32 v42, 0x880, v35
	global_store_short_d16_hi v42, v38, s[24:25]
	s_waitcnt lgkmcnt(2)
	v_fma_f32 v38, v148, v147, v144
	v_mul_f32_e32 v138, v138, v228
	v_rcp_f32_e32 v133, v133
	v_bfe_u32 v42, v38, 16, 1
	v_add3_u32 v38, v38, v42, s66
	v_add_u32_e32 v42, 0x1080, v35
	v_fmac_f32_e32 v145, v139, v138
	v_rcp_f32_e32 v126, v126
	global_store_short_d16_hi v42, v38, s[24:25]
	v_bfe_u32 v38, v145, 16, 1
	v_mul_f32_e32 v131, v131, v228
	v_add3_u32 v38, v145, v38, s66
	v_add_u32_e32 v42, 0x1880, v35
	global_store_short_d16_hi v42, v38, s[24:25]
	s_waitcnt lgkmcnt(1)
	v_fma_f32 v38, v133, v131, v160
	v_mul_f32_e32 v124, v124, v228
	v_rcp_f32_e32 v121, v121
	v_rcp_f32_e32 v114, v114
	v_bfe_u32 v42, v38, 16, 1
	v_add3_u32 v38, v38, v42, s66
	v_add_u32_e32 v42, 0x4080, v35
	v_fmac_f32_e32 v161, v126, v124
	global_store_short_d16_hi v42, v38, s[24:25]
	v_bfe_u32 v38, v161, 16, 1
	v_mul_f32_e32 v120, v120, v228
	v_mul_f32_e32 v113, v113, v228
	v_add3_u32 v38, v161, v38, s66
	v_add_u32_e32 v42, 0x4880, v35
	global_store_short_d16_hi v42, v38, s[24:25]
	s_waitcnt lgkmcnt(0)
	v_fma_f32 v38, v121, v120, v164
	v_fmac_f32_e32 v165, v114, v113
	ds_read2st64_b32 v[112:113], v68 offset0:40 offset1:41
	v_rcp_f32_e32 v108, v108
	v_bfe_u32 v42, v38, 16, 1
	v_add3_u32 v38, v38, v42, s66
	v_add_u32_e32 v42, 0x5080, v35
	v_rcp_f32_e32 v102, v102
	global_store_short_d16_hi v42, v38, s[24:25]
	v_bfe_u32 v38, v165, 16, 1
	v_mul_f32_e32 v106, v106, v228
	v_add3_u32 v38, v165, v38, s66
	v_add_u32_e32 v42, 0x5880, v35
	global_store_short_d16_hi v42, v38, s[24:25]
	s_waitcnt lgkmcnt(0)
	v_fma_f32 v38, v108, v106, v112
	v_mul_f32_e32 v65, v65, v228
	v_rcp_f32_e32 v62, v62
	v_bfe_u32 v42, v38, 16, 1
	ds_read2st64_b32 v[118:119], v68 offset0:42 offset1:43
	ds_read2st64_b32 v[120:121], v68 offset0:44 offset1:45
	ds_read2st64_b32 v[124:125], v68 offset0:46 offset1:47
	v_add3_u32 v38, v38, v42, s66
	v_add_u32_e32 v42, 0x8080, v35
	v_fmac_f32_e32 v113, v102, v65
	v_rcp_f32_e32 v56, v56
	global_store_short_d16_hi v42, v38, s[24:25]
	v_bfe_u32 v38, v113, 16, 1
	v_mul_f32_e32 v60, v60, v228
	v_add3_u32 v38, v113, v38, s66
	v_add_u32_e32 v42, 0x8880, v35
	global_store_short_d16_hi v42, v38, s[24:25]
	s_waitcnt lgkmcnt(2)
	v_fma_f32 v38, v62, v60, v118
	v_mul_f32_e32 v55, v55, v228
	v_rcp_f32_e32 v52, v52
	v_bfe_u32 v42, v38, 16, 1
	v_add3_u32 v38, v38, v42, s66
	v_add_u32_e32 v42, 0x9080, v35
	v_fmac_f32_e32 v119, v56, v55
	v_rcp_f32_e32 v47, v47
	global_store_short_d16_hi v42, v38, s[24:25]
	v_bfe_u32 v38, v119, 16, 1
	v_mul_f32_e32 v50, v50, v228
	v_add3_u32 v38, v119, v38, s66
	v_add_u32_e32 v42, 0x9880, v35
	global_store_short_d16_hi v42, v38, s[24:25]
	s_waitcnt lgkmcnt(1)
; __device__ __forceinline__ void attn_unit_pp(int b, int h, int qb, int par, const bf16_t* __restrict__ QBp, const bf16_t* __restrict__ KBp, const bf16_t* __restrict__ VBp, ...
;     ...
; #pragma unroll
;     for (int d0 = 0; d0 < 4; ++d0)
; #pragma unroll
;       for (int r = 0; r < 16; ++r) { const int ro = (r & 3) + 8 * (r >> 2);
;         const float val = o[d0][r] + pgs[(d0 * 16 + r) * 64];
;         unsigned u = __float_as_uint(val); u = (u + 0x7fffu + ((u >> 16) & 1u)) >> 16;
;         MIX_ST(ro, d0 * 32, (unsigned short)u); }
	v_fma_f32 v38, v52, v50, v120
	v_mul_f32_e32 v45, v45, v228
	v_bfe_u32 v42, v38, 16, 1
	v_add3_u32 v38, v38, v42, s66
	v_add_u32_e32 v42, 0xc080, v35
	v_fmac_f32_e32 v121, v47, v45
	global_store_short_d16_hi v42, v38, s[24:25]
	v_bfe_u32 v38, v121, 16, 1
	v_mul_f32_e32 v41, v41, v228
	v_add3_u32 v38, v121, v38, s66
	v_add_u32_e32 v42, 0xc880, v35
	global_store_short_d16_hi v42, v38, s[24:25]
	s_waitcnt lgkmcnt(0)
	v_fma_f32 v38, v153, v41, v124
	ds_read2st64_b32 v[46:47], v68 offset0:48 offset1:49
	v_bfe_u32 v41, v38, 16, 1
	v_add3_u32 v38, v38, v41, s66
	v_add_u32_e32 v41, 0xd080, v35
	v_fmac_f32_e32 v125, v218, v217
	s_waitcnt vmcnt(46)
	v_mul_f32_e32 v227, 0x3f4ccccd, v237
	global_store_short_d16_hi v41, v38, s[24:25]
	v_bfe_u32 v38, v125, 16, 1
	v_mul_f32_e32 v159, v159, v227
	v_add3_u32 v38, v125, v38, s66
	v_add_u32_e32 v41, 0xd880, v35
	global_store_short_d16_hi v41, v38, s[24:25]
	s_waitcnt lgkmcnt(0)
	v_fma_f32 v41, v157, v159, v46
	v_mul_f32_e32 v149, v149, v227
	v_bfe_u32 v42, v41, 16, 1
	v_add_u32_e32 v38, 0xc0, v35
	ds_read2st64_b32 v[50:51], v68 offset0:50 offset1:51
	ds_read2st64_b32 v[60:61], v68 offset0:52 offset1:53
	ds_read2st64_b32 v[102:103], v68 offset0:54 offset1:55
	v_add3_u32 v41, v41, v42, s66
	v_fmac_f32_e32 v47, v151, v149
	global_store_short_d16_hi v38, v41, s[24:25]
	v_bfe_u32 v38, v47, 16, 1
	v_mul_f32_e32 v143, v143, v227
	v_add3_u32 v38, v47, v38, s66
	v_add_u32_e32 v41, 0x8c0, v35
	global_store_short_d16_hi v41, v38, s[24:25]
	s_waitcnt lgkmcnt(2)
	v_fma_f32 v38, v141, v143, v50
	v_mul_f32_e32 v134, v134, v227
	v_bfe_u32 v41, v38, 16, 1
	v_add3_u32 v38, v38, v41, s66
	v_add_u32_e32 v41, 0x10c0, v35
	v_fmac_f32_e32 v51, v137, v134
	global_store_short_d16_hi v41, v38, s[24:25]
	v_bfe_u32 v38, v51, 16, 1
	v_mul_f32_e32 v130, v130, v227
	v_add3_u32 v38, v51, v38, s66
	v_add_u32_e32 v41, 0x18c0, v35
	global_store_short_d16_hi v41, v38, s[24:25]
	s_waitcnt lgkmcnt(1)
	v_fma_f32 v38, v129, v130, v60
	v_mul_f32_e32 v122, v122, v227
	v_bfe_u32 v41, v38, 16, 1
	v_add3_u32 v38, v38, v41, s66
	v_add_u32_e32 v41, 0x40c0, v35
	v_fmac_f32_e32 v61, v123, v122
	global_store_short_d16_hi v41, v38, s[24:25]
	v_bfe_u32 v38, v61, 16, 1
	v_mul_f32_e32 v117, v117, v227
	v_add3_u32 v38, v61, v38, s66
	v_add_u32_e32 v41, 0x48c0, v35
	global_store_short_d16_hi v41, v38, s[24:25]
	s_waitcnt lgkmcnt(0)
	v_fma_f32 v38, v115, v117, v102
	ds_read2st64_b32 v[46:47], v68 offset0:56 offset1:57
	v_mul_f32_e32 v109, v109, v227
	v_bfe_u32 v41, v38, 16, 1
	v_add3_u32 v38, v38, v41, s66
	v_add_u32_e32 v41, 0x50c0, v35
	v_fmac_f32_e32 v103, v110, v109
	global_store_short_d16_hi v41, v38, s[24:25]
	v_bfe_u32 v38, v103, 16, 1
	v_mul_f32_e32 v105, v105, v227
	v_add3_u32 v38, v103, v38, s66
	v_add_u32_e32 v41, 0x58c0, v35
	global_store_short_d16_hi v41, v38, s[24:25]
	s_waitcnt lgkmcnt(0)
	v_fma_f32 v38, v104, v105, v46
	v_mul_f32_e32 v63, v63, v227
	v_bfe_u32 v41, v38, 16, 1
	ds_read2st64_b32 v[50:51], v68 offset0:58 offset1:59
	ds_read2st64_b32 v[60:61], v68 offset0:60 offset1:61
	ds_read2st64_b32 v[102:103], v68 offset0:62 offset1:63
	v_add3_u32 v38, v38, v41, s66
	v_add_u32_e32 v41, 0x80c0, v35
	v_fmac_f32_e32 v47, v64, v63
	global_store_short_d16_hi v41, v38, s[24:25]
	v_bfe_u32 v38, v47, 16, 1
	v_mul_f32_e32 v59, v59, v227
	v_add3_u32 v38, v47, v38, s66
	v_add_u32_e32 v41, 0x88c0, v35
	global_store_short_d16_hi v41, v38, s[24:25]
	s_waitcnt lgkmcnt(2)
	v_fma_f32 v38, v57, v59, v50
	v_mul_f32_e32 v53, v53, v227
	v_bfe_u32 v41, v38, 16, 1
	v_add3_u32 v38, v38, v41, s66
	v_add_u32_e32 v41, 0x90c0, v35
	v_fmac_f32_e32 v51, v54, v53
	global_store_short_d16_hi v41, v38, s[24:25]
	v_bfe_u32 v38, v51, 16, 1
	v_mul_f32_e32 v49, v49, v227
	v_add3_u32 v38, v51, v38, s66
	v_add_u32_e32 v41, 0x98c0, v35
	global_store_short_d16_hi v41, v38, s[24:25]
	s_waitcnt lgkmcnt(1)
	v_fma_f32 v38, v48, v49, v60
	v_mul_f32_e32 v43, v43, v227
	v_rcp_f32_e32 v37, v37
	v_bfe_u32 v41, v38, 16, 1
	v_add3_u32 v38, v38, v41, s66
	v_add_u32_e32 v41, 0xc0c0, v35
	v_fmac_f32_e32 v61, v44, v43
	global_store_short_d16_hi v41, v38, s[24:25]
	v_bfe_u32 v38, v61, 16, 1
	v_mul_f32_e32 v40, v40, v227
	v_mul_f32_e32 v36, v227, v36
	v_add3_u32 v38, v61, v38, s66
	v_add_u32_e32 v41, 0xc8c0, v35
	global_store_short_d16_hi v41, v38, s[24:25]
	s_waitcnt lgkmcnt(0)
	v_fma_f32 v38, v39, v40, v102
	v_fmac_f32_e32 v103, v37, v36
	v_bfe_u32 v39, v38, 16, 1
	v_bfe_u32 v36, v103, 16, 1
	v_add3_u32 v38, v38, v39, s66
	v_add_u32_e32 v39, 0xd0c0, v35
	v_add3_u32 v36, v103, v36, s66
	v_add_u32_e32 v35, 0xd8c0, v35
	global_store_short_d16_hi v39, v38, s[24:25]
	global_store_short_d16_hi v35, v36, s[24:25]
	s_cbranch_execnz .LBB0_338

; __device__ __forceinline__ float bf_lo(unsigned w) { return __uint_as_float(w << 16); }
; __device__ __forceinline__ float bf_hi(unsigned w) { return __uint_as_float(w & 0xffff0000u); }
; #define GAS __attribute__((address_space(1)))
; __global__ void __launch_bounds__(NWAVES * 64) mega_fwd(Args args) {
;     ...
;     for (int row = gw; row < MROWS; row += NGW) {
;         const int b = row >> 11; const float* mb = MOD + (size_t)b * NMOD;
;         GAS f32x4* zr = (GAS f32x4*)(out + (size_t)row * D) + lane;
;         const GAS f32x4* xr = (const GAS f32x4*)(x + (size_t)row * D) + lane;
;         const GAS unsigned long long* yr = (const GAS unsigned long long*)(Y1 + (size_t)row * D) + lane;
;         f32x4 v[4]; float s = 0.f;
; #pragma unroll
;         for (int j = 0; j < 4; ++j) { const f32x4 xv = __builtin_nontemporal_load(&xr[64 * j]); const unsigned long long yy = __builtin_nontemporal_load(&yr[64 * j]); const unsigned ylo = (unsigned)yy, yhi = (unsigned)(yy >> 32);
;             v[j] = xv * ALPHA + (f32x4){pg8::bf_lo(ylo), pg8::bf_hi(ylo), pg8::bf_lo(yhi), pg8::bf_hi(yhi)};
;             s += (v[j].x + v[j].y) + (v[j].z + v[j].w); }
;         float mean = wave_sum(s, lane) * (1.f / D), s2 = 0.f;
; #pragma unroll
;         for (int j = 0; j < 4; ++j) { v[j] = v[j] - mean; s2 += (v[j].x * v[j].x + v[j].y * v[j].y) + (v[j].z * v[j].z + v[j].w * v[j].w); }
.LBB0_543:
	global_load_dwordx2 v[32:33], v[38:39], off offset:-1536 nt
	global_load_dwordx2 v[34:35], v[38:39], off offset:-1024 nt
	global_load_dwordx2 v[46:47], v[38:39], off offset:-512 nt
	global_load_dwordx2 v[48:49], v[38:39], off nt
	v_lshl_add_u64 v[50:51], s[10:11], 0, v[36:37]
	global_load_dwordx4 v[62:65], v[50:51], off nt
	global_load_dwordx4 v[66:69], v[50:51], off offset:1024 nt
	global_load_dwordx4 v[70:73], v[50:51], off offset:2048 nt
	global_load_dwordx4 v[74:77], v[50:51], off offset:3072 nt
	s_ashr_i32 s0, s13, 11
	s_mul_hi_i32 s1, s0, 0x6000
	s_mulk_i32 s0, 0x6000
	s_add_u32 s0, s28, s0
	v_add_co_u32_e32 v44, vcc, s35, v38
	s_addc_u32 s1, s29, s1
	s_nop 0
	v_addc_co_u32_e32 v45, vcc, -1, v39, vcc
	v_lshl_add_u64 v[78:79], s[0:1], 0, v[40:41]
	v_lshl_add_u64 v[50:51], v[78:79], 0, s[14:15]
	v_lshl_add_u64 v[52:53], v[78:79], 0, s[16:17]
	v_add_co_u32_e32 v78, vcc, s30, v78
	v_lshl_add_u64 v[42:43], s[2:3], 0, v[36:37]
	s_nop 0
	v_addc_co_u32_e32 v79, vcc, 0, v79, vcc
	v_lshl_add_u64 v[38:39], v[38:39], 0, s[8:9]
	s_waitcnt vmcnt(7)
	v_lshlrev_b32_e32 v80, 16, v32
	v_and_b32_e32 v81, 0xffff0000, v32
	v_lshlrev_b32_e32 v32, 16, v33
	v_and_b32_e32 v33, 0xffff0000, v33
	s_waitcnt vmcnt(6)
	v_lshlrev_b32_e32 v82, 16, v34
	v_and_b32_e32 v83, 0xffff0000, v34
	v_lshlrev_b32_e32 v34, 16, v35
	v_and_b32_e32 v35, 0xffff0000, v35
	s_waitcnt vmcnt(5)
	v_lshlrev_b32_e32 v84, 16, v46
	v_and_b32_e32 v85, 0xffff0000, v46
	v_lshlrev_b32_e32 v46, 16, v47
	v_and_b32_e32 v47, 0xffff0000, v47
	s_waitcnt vmcnt(4)
	v_lshlrev_b32_e32 v86, 16, v48
	v_and_b32_e32 v87, 0xffff0000, v48
	v_lshlrev_b32_e32 v48, 16, v49
	v_and_b32_e32 v49, 0xffff0000, v49
	s_waitcnt vmcnt(3)
	v_pk_fma_f32 v[32:33], v[64:65], s[12:13], v[32:33] op_sel_hi:[1,0,1]
	v_pk_fma_f32 v[62:63], v[62:63], s[12:13], v[80:81] op_sel_hi:[1,0,1]
	s_waitcnt vmcnt(2)
	v_pk_fma_f32 v[34:35], v[68:69], s[12:13], v[34:35] op_sel_hi:[1,0,1]
	v_pk_fma_f32 v[64:65], v[66:67], s[12:13], v[82:83] op_sel_hi:[1,0,1]
	s_waitcnt vmcnt(1)
	v_pk_fma_f32 v[46:47], v[72:73], s[12:13], v[46:47] op_sel_hi:[1,0,1]
	v_pk_fma_f32 v[66:67], v[70:71], s[12:13], v[84:85] op_sel_hi:[1,0,1]
	s_waitcnt vmcnt(0)
	v_pk_fma_f32 v[48:49], v[76:77], s[12:13], v[48:49] op_sel_hi:[1,0,1]
	v_pk_fma_f32 v[68:69], v[74:75], s[12:13], v[86:87] op_sel_hi:[1,0,1]
	v_pk_mov_b32 v[70:71], v[62:63], v[32:33] op_sel:[1,0]
	v_mov_b32_e32 v72, v62
	v_mov_b32_e32 v73, v33
	v_pk_mov_b32 v[74:75], v[64:65], v[34:35] op_sel:[1,0]
	v_mov_b32_e32 v76, v64
	v_mov_b32_e32 v77, v35
	v_pk_add_f32 v[70:71], v[70:71], v[72:73]
	v_pk_add_f32 v[72:73], v[74:75], v[76:77]
	v_add_f32_e32 v76, v70, v71
	v_pk_add_f32 v[70:71], v[72:73], v[72:73] op_sel:[0,1] op_sel_hi:[1,0]
	v_add_f32_e32 v80, v66, v67
	v_add_f32_e32 v82, v46, v47
	v_mov_b32_e32 v85, v68
	v_mov_b32_e32 v81, v48
	v_mov_b32_e32 v83, v49
	v_add_f32_e32 v84, 0, v76
	v_mov_b32_e32 v71, v69
	v_pk_add_f32 v[74:75], v[80:81], v[82:83]
	v_pk_add_f32 v[70:71], v[84:85], v[70:71]
	s_add_i32 s13, s13, s34
	v_pk_add_f32 v[70:71], v[70:71], v[74:75]
	s_add_u32 s2, s2, s6
	v_add_f32_e32 v70, v70, v71
	s_addc_u32 s3, s3, s7
	s_add_u32 s10, s10, s6
	s_addc_u32 s11, s11, s7
	s_cmp_gt_i32 s13, 0xffff
	s_waitcnt lgkmcnt(0)
	s_nop 1
	v_add_f32_dpp v70, v70, v70 quad_perm:[1,0,3,2] row_mask:0xf bank_mask:0xf
	s_waitcnt lgkmcnt(0)
	s_nop 1
	v_add_f32_dpp v70, v70, v70 quad_perm:[2,3,0,1] row_mask:0xf bank_mask:0xf
	s_waitcnt lgkmcnt(0)
	s_nop 1
	v_add_f32_dpp v70, v70, v70 row_half_mirror row_mask:0xf bank_mask:0xf
	s_waitcnt lgkmcnt(0)
	s_nop 1
	v_add_f32_dpp v70, v70, v70 row_mirror row_mask:0xf bank_mask:0xf
	s_waitcnt lgkmcnt(0)
	v_mov_b32_e32 v71, v70
	s_nop 1
	v_permlane16_swap_b32_e32 v70, v71
	v_add_f32_e32 v70, v70, v71
	s_waitcnt lgkmcnt(0)
	v_mov_b32_e32 v71, v70
	s_nop 1
	v_permlane32_swap_b32_e32 v70, v71
	v_add_f32_e32 v70, v70, v71
	v_fmamk_f32 v63, v70, 0xba800000, v63
	v_fmac_f32_e32 v62, 0xba800000, v70
	v_fmamk_f32 v33, v70, 0xba800000, v33
	v_fmac_f32_e32 v32, 0xba800000, v70
	v_fmamk_f32 v65, v70, 0xba800000, v65
	v_fmac_f32_e32 v64, 0xba800000, v70
	v_fmamk_f32 v35, v70, 0xba800000, v35
	v_fmac_f32_e32 v34, 0xba800000, v70
	v_fmamk_f32 v67, v70, 0xba800000, v67
	v_fmac_f32_e32 v66, 0xba800000, v70
	v_fmamk_f32 v47, v70, 0xba800000, v47
	v_fmac_f32_e32 v46, 0xba800000, v70
	v_fmamk_f32 v49, v70, 0xba800000, v49
	v_fmac_f32_e32 v48, 0xba800000, v70
	v_fmamk_f32 v69, v70, 0xba800000, v69
	v_fmac_f32_e32 v68, 0xba800000, v70
	v_pk_mul_f32 v[70:71], v[32:33], v[32:33]
	v_pk_mul_f32 v[72:73], v[62:63], v[62:63]
	v_pk_mul_f32 v[74:75], v[34:35], v[34:35]
	v_pk_mul_f32 v[76:77], v[64:65], v[64:65]
	v_pk_mov_b32 v[84:85], v[72:73], v[70:71] op_sel:[1,0]
	v_mov_b32_e32 v73, v71
	v_pk_mov_b32 v[70:71], v[76:77], v[74:75] op_sel:[1,0]
	v_mov_b32_e32 v77, v75
	v_mul_f32_e32 v83, v68, v68
	v_mul_f32_e32 v80, v67, v67
	v_mul_f32_e32 v82, v47, v47
	v_pk_add_f32 v[72:73], v[84:85], v[72:73]
	v_pk_add_f32 v[70:71], v[70:71], v[76:77]
	v_mul_f32_e32 v86, v69, v69
	v_mul_f32_e32 v87, v48, v48
	v_mul_f32_e32 v88, v49, v49
	v_pk_fma_f32 v[74:75], v[66:67], v[66:67], v[80:81] op_sel_hi:[1,1,0]
	v_pk_fma_f32 v[80:81], v[46:47], v[46:47], v[82:83] op_sel_hi:[1,1,0]
	v_pk_add_f32 v[72:73], v[72:73], v[72:73] op_sel:[0,1] op_sel_hi:[1,0]
	v_pk_add_f32 v[70:71], v[70:71], v[70:71] op_sel:[0,1] op_sel_hi:[1,0]
	v_mov_b32_e32 v75, v87
	v_mov_b32_e32 v81, v88
	v_mov_b32_e32 v73, v83
	v_mov_b32_e32 v71, v86
	v_pk_add_f32 v[74:75], v[74:75], v[80:81]
	v_pk_add_f32 v[70:71], v[72:73], v[70:71]
	s_nop 0
	v_pk_add_f32 v[70:71], v[70:71], v[74:75]
	s_nop 0
	v_add_f32_e32 v70, v70, v71
	s_waitcnt lgkmcnt(0)
; __global__ void __launch_bounds__(NWAVES * 64) mega_fwd(Args args) {
;     ...
;         float rstd = 1.f / sqrtf(wave_sum(s2, lane) * (1.f / D) + LN_EPS);
;         s = 0.f;
; #pragma unroll
;         for (int j = 0; j < 4; ++j) { const f32x4 gg = g1v[j], bb = b1v[j];
;             v[j] = v[j] * rstd * gg + bb; __builtin_nontemporal_store(v[j], &zr[64 * j]); s += (v[j].x + v[j].y) + (v[j].z + v[j].w); }
;         mean = wave_sum(s, lane) * (1.f / D); s2 = 0.f;
; #pragma unroll
;         for (int j = 0; j < 4; ++j) { v[j] = v[j] - mean; s2 += (v[j].x * v[j].x + v[j].y * v[j].y) + (v[j].z * v[j].z + v[j].w * v[j].w); }
;         rstd = 1.f / sqrtf(wave_sum(s2, lane) * (1.f / D) + LN_EPS);
	s_nop 1
	v_add_f32_dpp v70, v70, v70 quad_perm:[1,0,3,2] row_mask:0xf bank_mask:0xf
	s_waitcnt lgkmcnt(0)
	s_nop 1
	v_add_f32_dpp v70, v70, v70 quad_perm:[2,3,0,1] row_mask:0xf bank_mask:0xf
	s_waitcnt lgkmcnt(0)
	s_nop 1
	v_add_f32_dpp v70, v70, v70 row_half_mirror row_mask:0xf bank_mask:0xf
	s_waitcnt lgkmcnt(0)
	s_nop 1
	v_add_f32_dpp v70, v70, v70 row_mirror row_mask:0xf bank_mask:0xf
	s_waitcnt lgkmcnt(0)
	v_mov_b32_e32 v71, v70
	s_nop 1
	v_permlane16_swap_b32_e32 v70, v71
	v_add_f32_e32 v70, v70, v71
	s_waitcnt lgkmcnt(0)
	v_mov_b32_e32 v71, v70
	s_nop 1
	v_permlane32_swap_b32_e32 v70, v71
	v_add_f32_e32 v70, v70, v71
	v_fmamk_f32 v70, v70, 0x3a800000, v60
	v_mul_f32_e32 v71, 0x4f800000, v70
	v_cmp_gt_f32_e32 vcc, s23, v70
	s_nop 1
	v_cndmask_b32_e32 v70, v70, v71, vcc
	v_sqrt_f32_e32 v71, v70
	s_nop 0
	v_add_u32_e32 v72, -1, v71
	v_add_u32_e32 v73, 1, v71
	v_fma_f32 v74, -v72, v71, v70
	v_fma_f32 v75, -v73, v71, v70
	v_cmp_ge_f32_e64 s[0:1], 0, v74
	s_nop 1
	v_cndmask_b32_e64 v71, v71, v72, s[0:1]
	v_cmp_lt_f32_e64 s[0:1], 0, v75
	s_nop 1
	v_cndmask_b32_e64 v71, v71, v73, s[0:1]
	v_mul_f32_e32 v72, 0x37800000, v71
	v_cndmask_b32_e32 v71, v71, v72, vcc
	v_cmp_class_f32_e32 vcc, v70, v61
	s_nop 1
	v_cndmask_b32_e32 v70, v71, v70, vcc
	v_div_scale_f32 v71, s[0:1], v70, v70, 1.0
	v_rcp_f32_e32 v73, v71
	v_div_scale_f32 v72, vcc, 1.0, v70, 1.0
	v_fma_f32 v74, -v71, v73, 1.0
	v_fmac_f32_e32 v73, v74, v73
	v_mul_f32_e32 v74, v72, v73
	v_fma_f32 v75, -v71, v74, v72
	v_fmac_f32_e32 v74, v75, v73
	v_fma_f32 v71, -v71, v74, v72
	v_div_fmas_f32 v71, v71, v73, v74
	v_div_fixup_f32 v70, v71, v70, 1.0
	v_pk_mul_f32 v[32:33], v[70:71], v[32:33] op_sel_hi:[0,1]
	v_pk_mul_f32 v[62:63], v[70:71], v[62:63] op_sel_hi:[0,1]
	v_pk_mul_f32 v[34:35], v[70:71], v[34:35] op_sel_hi:[0,1]
	v_pk_mul_f32 v[64:65], v[70:71], v[64:65] op_sel_hi:[0,1]
	v_pk_mul_f32 v[72:73], v[70:71], v[46:47] op_sel_hi:[0,1]
	v_pk_mul_f32 v[66:67], v[70:71], v[66:67] op_sel_hi:[0,1]
	v_pk_mul_f32 v[74:75], v[70:71], v[68:69] op_sel_hi:[0,1]
	v_pk_mul_f32 v[70:71], v[70:71], v[48:49] op_sel_hi:[0,1]
	v_pk_fma_f32 v[46:47], v[62:63], v[0:1], v[4:5]
	v_pk_fma_f32 v[48:49], v[32:33], v[2:3], v[6:7]
	v_pk_fma_f32 v[62:63], v[64:65], v[8:9], v[12:13]
	v_pk_fma_f32 v[64:65], v[34:35], v[10:11], v[14:15]
	v_pk_fma_f32 v[66:67], v[66:67], v[16:17], v[20:21]
	v_pk_fma_f32 v[68:69], v[72:73], v[18:19], v[22:23]
	v_pk_fma_f32 v[34:35], v[70:71], v[26:27], v[30:31]
	v_pk_fma_f32 v[32:33], v[74:75], v[24:25], v[28:29]
	v_pk_mov_b32 v[70:71], v[46:47], v[48:49] op_sel:[1,0]
	v_mov_b32_e32 v72, v46
	v_mov_b32_e32 v73, v49
	v_pk_mov_b32 v[74:75], v[62:63], v[64:65] op_sel:[1,0]
	v_mov_b32_e32 v76, v62
	v_mov_b32_e32 v77, v65
	global_store_dwordx4 v[42:43], v[46:49], off nt
	global_store_dwordx4 v[42:43], v[62:65], off offset:1024 nt
	global_store_dwordx4 v[42:43], v[66:69], off offset:2048 nt
	global_store_dwordx4 v[42:43], v[32:35], off offset:3072 nt
	v_pk_add_f32 v[84:85], v[70:71], v[72:73]
	v_pk_add_f32 v[86:87], v[74:75], v[76:77]
	global_load_dwordx4 v[70:73], v[78:79], off offset:-4096
	global_load_dwordx4 v[74:77], v[78:79], off
	v_add_f32_e32 v42, v84, v85
	v_pk_add_f32 v[78:79], v[86:87], v[86:87] op_sel:[0,1] op_sel_hi:[1,0]
	v_add_f32_e32 v80, v66, v67
	v_add_f32_e32 v82, v68, v69
	v_mov_b32_e32 v43, v32
	v_mov_b32_e32 v81, v34
	v_mov_b32_e32 v83, v35
	v_add_f32_e32 v42, 0, v42
	v_mov_b32_e32 v79, v33
	v_pk_add_f32 v[80:81], v[80:81], v[82:83]
	v_pk_add_f32 v[42:43], v[42:43], v[78:79]
	s_waitcnt vmcnt(0)
	v_pk_add_f32 v[74:75], v[74:75], 1.0 op_sel_hi:[1,0]
	v_pk_add_f32 v[42:43], v[42:43], v[80:81]
	s_nop 0
	v_add_f32_e32 v42, v42, v43
	s_waitcnt lgkmcnt(0)
	s_nop 1
	v_add_f32_dpp v42, v42, v42 quad_perm:[1,0,3,2] row_mask:0xf bank_mask:0xf
	s_waitcnt lgkmcnt(0)
	s_nop 1
	v_add_f32_dpp v42, v42, v42 quad_perm:[2,3,0,1] row_mask:0xf bank_mask:0xf
	s_waitcnt lgkmcnt(0)
	s_nop 1
	v_add_f32_dpp v42, v42, v42 row_half_mirror row_mask:0xf bank_mask:0xf
	s_waitcnt lgkmcnt(0)
	s_nop 1
	v_add_f32_dpp v42, v42, v42 row_mirror row_mask:0xf bank_mask:0xf
	s_waitcnt lgkmcnt(0)
	v_mov_b32_e32 v43, v42
	s_nop 1
	v_permlane16_swap_b32_e32 v42, v43
	v_add_f32_e32 v42, v42, v43
	s_waitcnt lgkmcnt(0)
	v_mov_b32_e32 v43, v42
	s_nop 1
	v_permlane32_swap_b32_e32 v42, v43
	v_add_f32_e32 v42, v42, v43
	v_fmamk_f32 v47, v42, 0xba800000, v47
	v_fmac_f32_e32 v46, 0xba800000, v42
	v_fmamk_f32 v49, v42, 0xba800000, v49
	v_fmac_f32_e32 v48, 0xba800000, v42
	v_fmamk_f32 v63, v42, 0xba800000, v63
	v_fmac_f32_e32 v62, 0xba800000, v42
	v_fmamk_f32 v65, v42, 0xba800000, v65
	v_fmac_f32_e32 v64, 0xba800000, v42
	v_fmamk_f32 v67, v42, 0xba800000, v67
	v_fmac_f32_e32 v66, 0xba800000, v42
	v_fmamk_f32 v69, v42, 0xba800000, v69
	v_fmac_f32_e32 v68, 0xba800000, v42
	v_fmamk_f32 v35, v42, 0xba800000, v35
	v_fmac_f32_e32 v34, 0xba800000, v42
	v_fmamk_f32 v33, v42, 0xba800000, v33
	v_fmac_f32_e32 v32, 0xba800000, v42
	v_pk_mul_f32 v[42:43], v[48:49], v[48:49]
	v_pk_mul_f32 v[78:79], v[46:47], v[46:47]
	v_pk_mul_f32 v[80:81], v[64:65], v[64:65]
	v_pk_mul_f32 v[82:83], v[62:63], v[62:63]
	v_pk_mov_b32 v[88:89], v[78:79], v[42:43] op_sel:[1,0]
	v_mov_b32_e32 v79, v43
	v_pk_mov_b32 v[42:43], v[82:83], v[80:81] op_sel:[1,0]
	v_mov_b32_e32 v83, v81
	v_mul_f32_e32 v87, v32, v32
	v_mul_f32_e32 v84, v67, v67
	v_mul_f32_e32 v86, v69, v69
	v_pk_add_f32 v[78:79], v[88:89], v[78:79]
	v_pk_add_f32 v[42:43], v[42:43], v[82:83]
	v_mul_f32_e32 v90, v33, v33
	v_mul_f32_e32 v91, v34, v34
	v_mul_f32_e32 v92, v35, v35
	v_pk_fma_f32 v[80:81], v[66:67], v[66:67], v[84:85] op_sel_hi:[1,1,0]
	v_pk_fma_f32 v[84:85], v[68:69], v[68:69], v[86:87] op_sel_hi:[1,1,0]
	v_pk_add_f32 v[78:79], v[78:79], v[78:79] op_sel:[0,1] op_sel_hi:[1,0]
	v_pk_add_f32 v[42:43], v[42:43], v[42:43] op_sel:[0,1] op_sel_hi:[1,0]
	v_mov_b32_e32 v81, v91
	v_mov_b32_e32 v85, v92
	v_mov_b32_e32 v79, v87
	v_mov_b32_e32 v43, v90
	v_pk_add_f32 v[80:81], v[80:81], v[84:85]
	v_pk_add_f32 v[42:43], v[78:79], v[42:43]
	s_nop 0
	v_pk_add_f32 v[42:43], v[42:43], v[80:81]
	s_nop 0
	v_add_f32_e32 v42, v42, v43
	s_waitcnt lgkmcnt(0)
; #define GAS __attribute__((address_space(1)))
; __device__ __forceinline__ unsigned pk2(float lo, float hi) { return f2bf(lo) | (f2bf(hi) << 16); }
; __global__ void __launch_bounds__(NWAVES * 64) mega_fwd(Args args) {
;     ...
;         mean = wave_sum(s, lane) * (1.f / D); s2 = 0.f;
; #pragma unroll
;         for (int j = 0; j < 4; ++j) { v[j] = v[j] - mean; s2 += (v[j].x * v[j].x + v[j].y * v[j].y) + (v[j].z * v[j].z + v[j].w * v[j].w); }
;         rstd = 1.f / sqrtf(wave_sum(s2, lane) * (1.f / D) + LN_EPS);
;         GAS unsigned long long* o8 = (GAS unsigned long long*)(HB + (size_t)row * D) + lane;
; #pragma unroll
;         for (int j = 0; j < 4; ++j) { const f32x4 sh = *(const f32x4*)(mb + 3072 + 256 * j + 4 * lane), sc = *(const f32x4*)(mb + 4096 + 256 * j + 4 * lane);
;             const f32x4 y = v[j] * rstd * (sc + 1.0f) + sh;
;             o8[64 * j] = (unsigned long long)pk2(y.x, y.y) | ((unsigned long long)pk2(y.z, y.w) << 32); }
	s_nop 1
	v_add_f32_dpp v42, v42, v42 quad_perm:[1,0,3,2] row_mask:0xf bank_mask:0xf
	s_waitcnt lgkmcnt(0)
	s_nop 1
	v_add_f32_dpp v42, v42, v42 quad_perm:[2,3,0,1] row_mask:0xf bank_mask:0xf
	s_waitcnt lgkmcnt(0)
	s_nop 1
	v_add_f32_dpp v42, v42, v42 row_half_mirror row_mask:0xf bank_mask:0xf
	s_waitcnt lgkmcnt(0)
	s_nop 1
	v_add_f32_dpp v42, v42, v42 row_mirror row_mask:0xf bank_mask:0xf
	s_waitcnt lgkmcnt(0)
	v_mov_b32_e32 v43, v42
	v_mov_b32_e32 v78, v42
	s_nop 1
	v_permlane16_swap_b32_e32 v78, v43
	v_add_f32_e32 v78, v78, v43
	v_pk_add_f32 v[42:43], v[76:77], 1.0 op_sel_hi:[1,0]
	s_waitcnt lgkmcnt(0)
	v_mov_b32_e32 v76, v78
	s_nop 1
	v_permlane32_swap_b32_e32 v78, v76
	v_add_f32_e32 v76, v78, v76
	v_fmamk_f32 v76, v76, 0x3a800000, v60
	v_mul_f32_e32 v77, 0x4f800000, v76
	v_cmp_gt_f32_e32 vcc, s23, v76
	s_nop 1
	v_cndmask_b32_e32 v76, v76, v77, vcc
	v_sqrt_f32_e32 v77, v76
	s_nop 0
	v_add_u32_e32 v78, -1, v77
	v_add_u32_e32 v79, 1, v77
	v_fma_f32 v80, -v78, v77, v76
	v_fma_f32 v81, -v79, v77, v76
	v_cmp_ge_f32_e64 s[0:1], 0, v80
	s_nop 1
	v_cndmask_b32_e64 v77, v77, v78, s[0:1]
	v_cmp_lt_f32_e64 s[0:1], 0, v81
	s_nop 1
	v_cndmask_b32_e64 v77, v77, v79, s[0:1]
	v_mul_f32_e32 v78, 0x37800000, v77
	v_cndmask_b32_e32 v77, v77, v78, vcc
	v_cmp_class_f32_e32 vcc, v76, v61
	s_nop 1
	v_cndmask_b32_e32 v76, v77, v76, vcc
	v_div_scale_f32 v77, s[0:1], v76, v76, 1.0
	v_rcp_f32_e32 v79, v77
	v_div_scale_f32 v78, vcc, 1.0, v76, 1.0
	v_fma_f32 v80, -v77, v79, 1.0
	v_fmac_f32_e32 v79, v80, v79
	v_mul_f32_e32 v80, v78, v79
	v_fma_f32 v81, -v77, v80, v78
	v_fmac_f32_e32 v80, v81, v79
	v_fma_f32 v77, -v77, v80, v78
	v_div_fmas_f32 v77, v77, v79, v80
	v_div_fixup_f32 v76, v77, v76, 1.0
	v_pk_mul_f32 v[46:47], v[76:77], v[46:47] op_sel_hi:[0,1]
	v_pk_mul_f32 v[48:49], v[76:77], v[48:49] op_sel_hi:[0,1]
	v_pk_fma_f32 v[42:43], v[48:49], v[42:43], v[72:73]
	v_pk_fma_f32 v[46:47], v[46:47], v[74:75], v[70:71]
	v_bfe_u32 v70, v42, 16, 1
	v_bfe_u32 v48, v46, 16, 1
	v_bfe_u32 v49, v47, 16, 1
	v_bfe_u32 v71, v43, 16, 1
	v_add3_u32 v46, v46, v48, s31
	v_add3_u32 v42, v42, v70, s31
	v_add3_u32 v47, v47, v49, s31
	v_add3_u32 v43, v43, v71, s31
	v_lshrrev_b32_e32 v46, 16, v46
	v_lshrrev_b32_e32 v48, 16, v42
	v_and_or_b32 v42, v47, s22, v46
	v_and_or_b32 v43, v43, s22, v48
	global_store_dwordx2 v[44:45], v[42:43], off offset:-1536
	global_load_dwordx4 v[46:49], v[52:53], off offset:1024
	global_load_dwordx4 v[70:73], v[50:51], off offset:1024
	v_pk_mul_f32 v[42:43], v[76:77], v[62:63] op_sel_hi:[0,1]
	v_pk_mul_f32 v[62:63], v[76:77], v[64:65] op_sel_hi:[0,1]
	v_pk_mul_f32 v[32:33], v[76:77], v[32:33] op_sel_hi:[0,1]
	v_pk_mul_f32 v[34:35], v[76:77], v[34:35] op_sel_hi:[0,1]
	s_waitcnt vmcnt(1)
	v_pk_add_f32 v[48:49], v[48:49], 1.0 op_sel_hi:[1,0]
	v_pk_add_f32 v[46:47], v[46:47], 1.0 op_sel_hi:[1,0]
	s_waitcnt vmcnt(0)
	v_pk_fma_f32 v[48:49], v[62:63], v[48:49], v[72:73]
	v_pk_fma_f32 v[42:43], v[42:43], v[46:47], v[70:71]
	v_bfe_u32 v62, v48, 16, 1
	v_bfe_u32 v46, v42, 16, 1
	v_bfe_u32 v47, v43, 16, 1
	v_bfe_u32 v63, v49, 16, 1
	v_add3_u32 v42, v42, v46, s31
	v_add3_u32 v46, v48, v62, s31
	v_add3_u32 v43, v43, v47, s31
	v_add3_u32 v47, v49, v63, s31
	v_lshrrev_b32_e32 v42, 16, v42
	v_lshrrev_b32_e32 v46, 16, v46
	v_and_or_b32 v42, v43, s22, v42
	v_and_or_b32 v43, v47, s22, v46
	global_store_dwordx2 v[44:45], v[42:43], off offset:-1024
	global_load_dwordx4 v[46:49], v[52:53], off offset:2048
	global_load_dwordx4 v[62:65], v[50:51], off offset:2048
	v_pk_mul_f32 v[42:43], v[76:77], v[66:67] op_sel_hi:[0,1]
	v_pk_mul_f32 v[66:67], v[76:77], v[68:69] op_sel_hi:[0,1]
	s_waitcnt vmcnt(1)
	v_pk_add_f32 v[48:49], v[48:49], 1.0 op_sel_hi:[1,0]
	v_pk_add_f32 v[46:47], v[46:47], 1.0 op_sel_hi:[1,0]
	s_waitcnt vmcnt(0)
	v_pk_fma_f32 v[48:49], v[66:67], v[48:49], v[64:65]
	v_pk_fma_f32 v[42:43], v[42:43], v[46:47], v[62:63]
	v_bfe_u32 v62, v48, 16, 1
	v_bfe_u32 v46, v42, 16, 1
	v_bfe_u32 v47, v43, 16, 1
	v_bfe_u32 v63, v49, 16, 1
	v_add3_u32 v42, v42, v46, s31
	v_add3_u32 v46, v48, v62, s31
	v_add3_u32 v43, v43, v47, s31
	v_add3_u32 v47, v49, v63, s31
	v_lshrrev_b32_e32 v42, 16, v42
	v_lshrrev_b32_e32 v46, 16, v46
	v_and_or_b32 v42, v43, s22, v42
	v_and_or_b32 v43, v47, s22, v46
	global_store_dwordx2 v[44:45], v[42:43], off offset:-512
	global_load_dwordx4 v[46:49], v[52:53], off offset:3072
	s_nop 0
	global_load_dwordx4 v[50:53], v[50:51], off offset:3072
	s_waitcnt vmcnt(1)
	v_pk_add_f32 v[42:43], v[48:49], 1.0 op_sel_hi:[1,0]
	v_pk_add_f32 v[46:47], v[46:47], 1.0 op_sel_hi:[1,0]
	s_waitcnt vmcnt(0)
	v_pk_fma_f32 v[34:35], v[34:35], v[42:43], v[52:53]
	v_pk_fma_f32 v[32:33], v[32:33], v[46:47], v[50:51]
	v_bfe_u32 v46, v34, 16, 1
	v_bfe_u32 v42, v32, 16, 1
	v_bfe_u32 v43, v33, 16, 1
	v_bfe_u32 v47, v35, 16, 1
	v_add3_u32 v32, v32, v42, s31
	v_add3_u32 v34, v34, v46, s31
	v_add3_u32 v33, v33, v43, s31
	v_add3_u32 v35, v35, v47, s31
	v_lshrrev_b32_e32 v32, 16, v32
	v_lshrrev_b32_e32 v34, 16, v34
	v_and_or_b32 v32, v33, s22, v32
	v_and_or_b32 v33, v35, s22, v34
	global_store_dwordx2 v[44:45], v[32:33], off
	s_cbranch_scc0 .LBB0_543

; __device__ __forceinline__ float bf_lo(unsigned w) { return __uint_as_float(w << 16); }
; __device__ __forceinline__ float bf_hi(unsigned w) { return __uint_as_float(w & 0xffff0000u); }
; #define GAS __attribute__((address_space(1)))
; __global__ void __launch_bounds__(NWAVES * 64) mega_fwd(Args args) {
;     ...
;     for (int row = gw; row < MROWS; row += NGW) {
;         GAS f32x4* zr = (GAS f32x4*)(out + (size_t)row * D) + lane;
;         const GAS unsigned long long* yr = (const GAS unsigned long long*)(Y2 + (size_t)row * D) + lane;
;         f32x4 v[4]; float s = 0.f;
; #pragma unroll
;         for (int j = 0; j < 4; ++j) { const f32x4 xv = __builtin_nontemporal_load(&zr[64 * j]); const unsigned long long yy = __builtin_nontemporal_load(&yr[64 * j]); const unsigned ylo = (unsigned)yy, yhi = (unsigned)(yy >> 32);
;             v[j] = xv * ALPHA + (f32x4){pg8::bf_lo(ylo), pg8::bf_hi(ylo), pg8::bf_lo(yhi), pg8::bf_hi(yhi)};
;             s += (v[j].x + v[j].y) + (v[j].z + v[j].w); }
;         const float mean = wave_sum(s, lane) * (1.f / D); float s2 = 0.f;
.LBB0_746:
	global_load_dwordx2 v[40:41], v[34:35], off offset:-1024 nt
	global_load_dwordx2 v[46:47], v[34:35], off offset:-512 nt
	global_load_dwordx2 v[64:65], v[34:35], off nt
	global_load_dwordx2 v[66:67], v[34:35], off offset:512 nt
	global_load_dwordx4 v[36:39], v[32:33], off offset:-3072 nt
	global_load_dwordx4 v[42:45], v[32:33], off offset:-2048 nt
	global_load_dwordx4 v[48:51], v[32:33], off offset:-1024 nt
	global_load_dwordx4 v[60:63], v[32:33], off nt
	v_lshl_add_u64 v[34:35], v[34:35], 0, s[4:5]
	s_waitcnt vmcnt(7)
	v_lshlrev_b32_e32 v68, 16, v40
	v_and_b32_e32 v69, 0xffff0000, v40
	v_lshlrev_b32_e32 v40, 16, v41
	v_and_b32_e32 v41, 0xffff0000, v41
	s_waitcnt vmcnt(6)
	v_lshlrev_b32_e32 v70, 16, v46
	v_and_b32_e32 v71, 0xffff0000, v46
	v_lshlrev_b32_e32 v72, 16, v47
	v_and_b32_e32 v73, 0xffff0000, v47
	s_waitcnt vmcnt(5)
	v_lshlrev_b32_e32 v74, 16, v64
	v_and_b32_e32 v75, 0xffff0000, v64
	v_lshlrev_b32_e32 v64, 16, v65
	v_and_b32_e32 v65, 0xffff0000, v65
	s_waitcnt vmcnt(4)
	v_lshlrev_b32_e32 v76, 16, v66
	v_and_b32_e32 v77, 0xffff0000, v66
	v_lshlrev_b32_e32 v66, 16, v67
	v_and_b32_e32 v67, 0xffff0000, v67
	s_waitcnt vmcnt(3)
	v_pk_fma_f32 v[40:41], v[38:39], s[6:7], v[40:41] op_sel_hi:[1,0,1]
	v_pk_fma_f32 v[46:47], v[36:37], s[6:7], v[68:69] op_sel_hi:[1,0,1]
	s_waitcnt vmcnt(2)
	v_pk_fma_f32 v[38:39], v[44:45], s[6:7], v[72:73] op_sel_hi:[1,0,1]
	v_pk_fma_f32 v[44:45], v[42:43], s[6:7], v[70:71] op_sel_hi:[1,0,1]
	s_waitcnt vmcnt(1)
	v_pk_fma_f32 v[36:37], v[50:51], s[6:7], v[64:65] op_sel_hi:[1,0,1]
	v_pk_fma_f32 v[42:43], v[48:49], s[6:7], v[74:75] op_sel_hi:[1,0,1]
	s_waitcnt vmcnt(0)
	v_pk_fma_f32 v[48:49], v[62:63], s[6:7], v[66:67] op_sel_hi:[1,0,1]
	v_pk_fma_f32 v[50:51], v[60:61], s[6:7], v[76:77] op_sel_hi:[1,0,1]
	v_pk_mov_b32 v[60:61], v[46:47], v[40:41] op_sel:[1,0]
	v_mov_b32_e32 v62, v46
	v_mov_b32_e32 v63, v41
	v_pk_mov_b32 v[64:65], v[44:45], v[38:39] op_sel:[1,0]
	v_mov_b32_e32 v66, v44
	v_mov_b32_e32 v67, v39
	v_pk_add_f32 v[60:61], v[60:61], v[62:63]
	v_pk_add_f32 v[62:63], v[64:65], v[66:67]
	v_add_f32_e32 v66, v60, v61
	v_pk_add_f32 v[60:61], v[62:63], v[62:63] op_sel:[0,1] op_sel_hi:[1,0]
	v_add_f32_e32 v68, v42, v43
	v_add_f32_e32 v70, v36, v37
	v_mov_b32_e32 v73, v50
	v_mov_b32_e32 v69, v48
	v_mov_b32_e32 v71, v49
	v_add_f32_e32 v72, 0, v66
	v_mov_b32_e32 v61, v51
	v_pk_add_f32 v[64:65], v[68:69], v[70:71]
	v_pk_add_f32 v[60:61], v[72:73], v[60:61]
	s_add_i32 s7, s7, s34
	v_pk_add_f32 v[60:61], v[60:61], v[64:65]
	s_cmp_gt_i32 s7, 0xffff
	v_add_f32_e32 v60, v60, v61
	s_waitcnt lgkmcnt(0)
	s_nop 1
	v_add_f32_dpp v60, v60, v60 quad_perm:[1,0,3,2] row_mask:0xf bank_mask:0xf
	s_waitcnt lgkmcnt(0)
	s_nop 1
	v_add_f32_dpp v60, v60, v60 quad_perm:[2,3,0,1] row_mask:0xf bank_mask:0xf
	s_waitcnt lgkmcnt(0)
	s_nop 1
	v_add_f32_dpp v60, v60, v60 row_half_mirror row_mask:0xf bank_mask:0xf
	s_waitcnt lgkmcnt(0)
	s_nop 1
	v_add_f32_dpp v60, v60, v60 row_mirror row_mask:0xf bank_mask:0xf
	s_waitcnt lgkmcnt(0)
	v_mov_b32_e32 v61, v60
	s_nop 1
	v_permlane16_swap_b32_e32 v60, v61
	v_add_f32_e32 v60, v60, v61
	s_waitcnt lgkmcnt(0)
; __global__ void __launch_bounds__(NWAVES * 64) mega_fwd(Args args) {
;     ...
;         const float mean = wave_sum(s, lane) * (1.f / D); float s2 = 0.f;
; #pragma unroll
;         for (int j = 0; j < 4; ++j) { v[j] = v[j] - mean; s2 += (v[j].x * v[j].x + v[j].y * v[j].y) + (v[j].z * v[j].z + v[j].w * v[j].w); }
;         const float rstd = 1.f / sqrtf(wave_sum(s2, lane) * (1.f / D) + LN_EPS);
; #pragma unroll
;         for (int j = 0; j < 4; ++j) { const f32x4 gg = g2v[j], bb = b2v[j];
;             __builtin_nontemporal_store(v[j] * rstd * gg + bb, &zr[64 * j]); }
	v_mov_b32_e32 v61, v60
	s_nop 1
	v_permlane32_swap_b32_e32 v60, v61
	v_add_f32_e32 v60, v60, v61
	v_fmamk_f32 v47, v60, 0xba800000, v47
	v_fmac_f32_e32 v46, 0xba800000, v60
	v_fmamk_f32 v41, v60, 0xba800000, v41
	v_fmac_f32_e32 v40, 0xba800000, v60
	v_fmamk_f32 v45, v60, 0xba800000, v45
	v_fmac_f32_e32 v44, 0xba800000, v60
	v_fmamk_f32 v39, v60, 0xba800000, v39
	v_fmac_f32_e32 v38, 0xba800000, v60
	v_fmamk_f32 v43, v60, 0xba800000, v43
	v_fmac_f32_e32 v42, 0xba800000, v60
	v_fmamk_f32 v37, v60, 0xba800000, v37
	v_fmac_f32_e32 v36, 0xba800000, v60
	v_fmamk_f32 v49, v60, 0xba800000, v49
	v_fmac_f32_e32 v48, 0xba800000, v60
	v_fmamk_f32 v51, v60, 0xba800000, v51
	v_fmac_f32_e32 v50, 0xba800000, v60
	v_pk_mul_f32 v[60:61], v[40:41], v[40:41]
	v_pk_mul_f32 v[62:63], v[46:47], v[46:47]
	v_pk_mul_f32 v[64:65], v[38:39], v[38:39]
	v_pk_mul_f32 v[66:67], v[44:45], v[44:45]
	v_pk_mov_b32 v[72:73], v[62:63], v[60:61] op_sel:[1,0]
	v_mov_b32_e32 v63, v61
	v_pk_mov_b32 v[60:61], v[66:67], v[64:65] op_sel:[1,0]
	v_mov_b32_e32 v67, v65
	v_mul_f32_e32 v71, v50, v50
	v_mul_f32_e32 v68, v43, v43
	v_mul_f32_e32 v70, v37, v37
	v_pk_add_f32 v[62:63], v[72:73], v[62:63]
	v_pk_add_f32 v[60:61], v[60:61], v[66:67]
	v_mul_f32_e32 v74, v51, v51
	v_mul_f32_e32 v75, v48, v48
	v_mul_f32_e32 v76, v49, v49
	v_pk_fma_f32 v[64:65], v[42:43], v[42:43], v[68:69] op_sel_hi:[1,1,0]
	v_pk_fma_f32 v[68:69], v[36:37], v[36:37], v[70:71] op_sel_hi:[1,1,0]
	v_pk_add_f32 v[62:63], v[62:63], v[62:63] op_sel:[0,1] op_sel_hi:[1,0]
	v_pk_add_f32 v[60:61], v[60:61], v[60:61] op_sel:[0,1] op_sel_hi:[1,0]
	v_mov_b32_e32 v65, v75
	v_mov_b32_e32 v69, v76
	v_mov_b32_e32 v63, v71
	v_mov_b32_e32 v61, v74
	v_pk_add_f32 v[64:65], v[64:65], v[68:69]
	v_pk_add_f32 v[60:61], v[62:63], v[60:61]
	s_nop 0
	v_pk_add_f32 v[60:61], v[60:61], v[64:65]
	s_nop 0
	v_add_f32_e32 v60, v60, v61
	s_waitcnt lgkmcnt(0)
	s_nop 1
	v_add_f32_dpp v60, v60, v60 quad_perm:[1,0,3,2] row_mask:0xf bank_mask:0xf
	s_waitcnt lgkmcnt(0)
	s_nop 1
	v_add_f32_dpp v60, v60, v60 quad_perm:[2,3,0,1] row_mask:0xf bank_mask:0xf
	s_waitcnt lgkmcnt(0)
	s_nop 1
	v_add_f32_dpp v60, v60, v60 row_half_mirror row_mask:0xf bank_mask:0xf
	s_waitcnt lgkmcnt(0)
	s_nop 1
	v_add_f32_dpp v60, v60, v60 row_mirror row_mask:0xf bank_mask:0xf
	s_waitcnt lgkmcnt(0)
	v_mov_b32_e32 v61, v60
	s_nop 1
	v_permlane16_swap_b32_e32 v60, v61
	v_add_f32_e32 v60, v60, v61
	s_waitcnt lgkmcnt(0)
	v_mov_b32_e32 v61, v60
	s_nop 1
	v_permlane32_swap_b32_e32 v60, v61
	v_add_f32_e32 v60, v60, v61
	v_fmamk_f32 v60, v60, 0x3a800000, v58
	v_mul_f32_e32 v61, 0x4f800000, v60
	v_cmp_gt_f32_e32 vcc, s8, v60
	s_nop 1
	v_cndmask_b32_e32 v60, v60, v61, vcc
	v_sqrt_f32_e32 v61, v60
	s_nop 0
	v_add_u32_e32 v62, -1, v61
	v_add_u32_e32 v63, 1, v61
	v_fma_f32 v64, -v62, v61, v60
	v_fma_f32 v65, -v63, v61, v60
	v_cmp_ge_f32_e64 s[0:1], 0, v64
	s_nop 1
	v_cndmask_b32_e64 v61, v61, v62, s[0:1]
	v_cmp_lt_f32_e64 s[0:1], 0, v65
	s_nop 1
	v_cndmask_b32_e64 v61, v61, v63, s[0:1]
	v_mul_f32_e32 v62, 0x37800000, v61
	v_cndmask_b32_e32 v61, v61, v62, vcc
	v_cmp_class_f32_e32 vcc, v60, v59
	s_nop 1
	v_cndmask_b32_e32 v60, v61, v60, vcc
	v_div_scale_f32 v61, s[0:1], v60, v60, 1.0
	v_rcp_f32_e32 v62, v61
	v_div_scale_f32 v63, vcc, 1.0, v60, 1.0
	v_fma_f32 v64, -v61, v62, 1.0
	v_fmac_f32_e32 v62, v64, v62
	v_mul_f32_e32 v64, v63, v62
	v_fma_f32 v65, -v61, v64, v63
	v_fmac_f32_e32 v64, v65, v62
	v_fma_f32 v61, -v61, v64, v63
	v_div_fmas_f32 v61, v61, v62, v64
	v_div_fixup_f32 v60, v61, v60, 1.0
	v_pk_mul_f32 v[46:47], v[60:61], v[46:47] op_sel_hi:[0,1]
	v_pk_mul_f32 v[40:41], v[60:61], v[40:41] op_sel_hi:[0,1]
	v_pk_mul_f32 v[44:45], v[60:61], v[44:45] op_sel_hi:[0,1]
	v_pk_mul_f32 v[62:63], v[60:61], v[38:39] op_sel_hi:[0,1]
	v_pk_mul_f32 v[64:65], v[60:61], v[42:43] op_sel_hi:[0,1]
	v_pk_mul_f32 v[66:67], v[60:61], v[36:37] op_sel_hi:[0,1]
	v_pk_mul_f32 v[68:69], v[60:61], v[50:51] op_sel_hi:[0,1]
	v_pk_mul_f32 v[48:49], v[60:61], v[48:49] op_sel_hi:[0,1]
	v_pk_fma_f32 v[38:39], v[40:41], v[2:3], v[6:7]
	v_pk_fma_f32 v[36:37], v[46:47], v[0:1], v[4:5]
	v_pk_fma_f32 v[42:43], v[62:63], v[10:11], v[14:15]
	v_pk_fma_f32 v[40:41], v[44:45], v[8:9], v[12:13]
	v_pk_fma_f32 v[46:47], v[66:67], v[18:19], v[22:23]
	v_pk_fma_f32 v[44:45], v[64:65], v[16:17], v[20:21]
	v_pk_fma_f32 v[50:51], v[48:49], v[26:27], v[30:31]
	v_pk_fma_f32 v[48:49], v[68:69], v[24:25], v[28:29]
	global_store_dwordx4 v[32:33], v[36:39], off offset:-3072 nt
	global_store_dwordx4 v[32:33], v[40:43], off offset:-2048 nt
	global_store_dwordx4 v[32:33], v[44:47], off offset:-1024 nt
	global_store_dwordx4 v[32:33], v[48:51], off nt
	v_lshl_add_u64 v[32:33], v[32:33], 0, s[2:3]
	s_cbranch_scc0 .LBB0_746
